# v11 plus: more packed f32 ops in the FFN-up epilogue (pk_mov bias init, pk_mul by -log2e, pk_add 1.0); FoX QK/PV fragment reads batched behind one lgkmcnt wait
# speedup vs baseline: 1.0008x; 1.0008x over previous
; #define LAS __attribute__((address_space(3)))
; #define PVS(s, pk) do { const bf16x8 a0_ = *(const LAS bf16x8*)(vb + (s) * 32), a1_ = *(const LAS bf16x8*)(vb + 32 * VT_STRIDE + (s) * 32); \
;             o0 = __builtin_amdgcn_mfma_f32_32x32x16_bf16(a0_, pk, o0, 0, 0, 0); o1 = __builtin_amdgcn_mfma_f32_32x32x16_bf16(a1_, pk, o1, 0, 0, 0); } while (0)
; #define PVS(s, pk) do { const bf16x8 a0_ = *(const LAS bf16x8*)(vb + (s) * 32), a1_ = *(const LAS bf16x8*)(vb + 32 * VT_STRIDE + (s) * 32); \
;             o0 = __builtin_amdgcn_mfma_f32_32x32x16_bf16(a0_, pk, o0, 0, 0, 0); o1 = __builtin_amdgcn_mfma_f32_32x32x16_bf16(a1_, pk, o1, 0, 0, 0); } while (0)
; #define PVS(s, pk) do { const bf16x8 a0_ = *(const LAS bf16x8*)(vb + (s) * 32), a1_ = *(const LAS bf16x8*)(vb + 32 * VT_STRIDE + (s) * 32); \
;             o0 = __builtin_amdgcn_mfma_f32_32x32x16_bf16(a0_, pk, o0, 0, 0, 0); o1 = __builtin_amdgcn_mfma_f32_32x32x16_bf16(a1_, pk, o1, 0, 0, 0); } while (0)
; #define PVS(s, pk) do { const bf16x8 a0_ = *(const LAS bf16x8*)(vb + (s) * 32), a1_ = *(const LAS bf16x8*)(vb + 32 * VT_STRIDE + (s) * 32); \
;             o0 = __builtin_amdgcn_mfma_f32_32x32x16_bf16(a0_, pk, o0, 0, 0, 0); o1 = __builtin_amdgcn_mfma_f32_32x32x16_bf16(a1_, pk, o1, 0, 0, 0); } while (0)
; template <int MODE>
; __device__ __forceinline__ void attn_unit(LAS unsigned char* lds, const AttnArgs& A, int qb) {
;     ...
;         if (active) {
;             f32x16 p0, p1;
; #pragma unroll
;             for (int r = 0; r < 16; ++r) { p0[r] = 0.f; p1[r] = 0.f; }
;             LAS unsigned char* kb = buf + kperm * 16 + hi * 1024;
; #pragma unroll
;             for (int d0 = 0; d0 < 4; ++d0) {
;                 const bf16x8 kf0 = *(const LAS bf16x8*)(kb + d0 * 2048), kf1 = *(const LAS bf16x8*)(kb + d0 * 2048 + 512);
;                 p0 = __builtin_amdgcn_mfma_f32_32x32x16_bf16(kf0, qr[d0], p0, 0, 0, 0);
;                 p1 = __builtin_amdgcn_mfma_f32_32x32x16_bf16(kf1, qr[d0], p1, 0, 0, 0);
;             }
;         if (prev_active) {
;             const LAS unsigned char* vb = lds + prevbuf + KB_BYTES + r32 * VT_STRIDE + hi * 16;
;     ...
;             PVS(0, pkP0); PVS(1, pkP1); PVS(2, pkP2); PVS(3, pkP3);
;     ...
;         }
.LBB0_973:
	s_andn2_b64 vcc, exec, s[28:29]
	s_cbranch_vccnz .LBB0_981
	s_nop 5
	v_add_u32_e32 v6, v186, v187
	s_and_b64 vcc, exec, s[10:11]
	ds_read_b128 v[2:5], v6
	ds_read_b128 v[8:11], v6 offset:512
	ds_read_b128 v[12:15], v6 offset:2048
	ds_read_b128 v[16:19], v6 offset:2560
	ds_read_b128 v[20:23], v6 offset:4096
	ds_read_b128 v[24:27], v6 offset:4608
	ds_read_b128 v[28:31], v6 offset:6144
	ds_read_b128 v[206:209], v6 offset:6656
	s_waitcnt lgkmcnt(0)
	v_mfma_f32_32x32x16_bf16 v[34:49], v[2:5], v[98:101], 0
	v_mfma_f32_32x32x16_bf16 v[50:65], v[8:11], v[98:101], 0
	v_mfma_f32_32x32x16_bf16 v[34:49], v[12:15], v[102:105], v[34:49]
	v_mfma_f32_32x32x16_bf16 v[50:65], v[16:19], v[102:105], v[50:65]
	v_mfma_f32_32x32x16_bf16 v[34:49], v[20:23], v[106:109], v[34:49]
	v_mfma_f32_32x32x16_bf16 v[50:65], v[24:27], v[106:109], v[50:65]
	v_mfma_f32_32x32x16_bf16 v[34:49], v[28:31], v[110:113], v[34:49]
	v_mfma_f32_32x32x16_bf16 v[50:65], v[206:209], v[110:113], v[50:65]
	s_cbranch_vccnz .LBB0_976
	v_add_u32_e32 v6, s2, v191
	ds_read_b128 v[2:5], v6 offset:8192
	ds_read_b128 v[8:11], v6 offset:12800
	ds_read_b128 v[12:15], v6 offset:8224
	ds_read_b128 v[16:19], v6 offset:12832
	ds_read_b128 v[20:23], v6 offset:8256
	ds_read_b128 v[24:27], v6 offset:12864
	ds_read_b128 v[28:31], v6 offset:12896
	ds_read_b128 v[206:209], v6 offset:8288
	s_waitcnt lgkmcnt(0)
	v_mfma_f32_32x32x16_bf16 v[82:97], v[2:5], v[150:153], v[82:97]
	v_mfma_f32_32x32x16_bf16 v[66:81], v[8:11], v[150:153], v[66:81]
	v_mfma_f32_32x32x16_bf16 v[82:97], v[12:15], v[142:145], v[82:97]
	v_mfma_f32_32x32x16_bf16 v[66:81], v[16:19], v[142:145], v[66:81]
	v_mfma_f32_32x32x16_bf16 v[82:97], v[20:23], v[146:149], v[82:97]
	v_mfma_f32_32x32x16_bf16 v[66:81], v[24:27], v[146:149], v[66:81]
	v_mfma_f32_32x32x16_bf16 v[66:81], v[28:31], v[138:141], v[66:81]
	v_mfma_f32_32x32x16_bf16 v[82:97], v[206:209], v[138:141], v[82:97]

; #define LAS __attribute__((address_space(3)))
; #define PVS(s, pk) do { const bf16x8 a0_ = *(const LAS bf16x8*)(vb + (s) * 32), a1_ = *(const LAS bf16x8*)(vb + 32 * VT_STRIDE + (s) * 32); \
;             o0 = __builtin_amdgcn_mfma_f32_32x32x16_bf16(a0_, pk, o0, 0, 0, 0); o1 = __builtin_amdgcn_mfma_f32_32x32x16_bf16(a1_, pk, o1, 0, 0, 0); } while (0)
; #define PVS(s, pk) do { const bf16x8 a0_ = *(const LAS bf16x8*)(vb + (s) * 32), a1_ = *(const LAS bf16x8*)(vb + 32 * VT_STRIDE + (s) * 32); \
;             o0 = __builtin_amdgcn_mfma_f32_32x32x16_bf16(a0_, pk, o0, 0, 0, 0); o1 = __builtin_amdgcn_mfma_f32_32x32x16_bf16(a1_, pk, o1, 0, 0, 0); } while (0)
; #define PVS(s, pk) do { const bf16x8 a0_ = *(const LAS bf16x8*)(vb + (s) * 32), a1_ = *(const LAS bf16x8*)(vb + 32 * VT_STRIDE + (s) * 32); \
;             o0 = __builtin_amdgcn_mfma_f32_32x32x16_bf16(a0_, pk, o0, 0, 0, 0); o1 = __builtin_amdgcn_mfma_f32_32x32x16_bf16(a1_, pk, o1, 0, 0, 0); } while (0)
; #define PVS(s, pk) do { const bf16x8 a0_ = *(const LAS bf16x8*)(vb + (s) * 32), a1_ = *(const LAS bf16x8*)(vb + 32 * VT_STRIDE + (s) * 32); \
;             o0 = __builtin_amdgcn_mfma_f32_32x32x16_bf16(a0_, pk, o0, 0, 0, 0); o1 = __builtin_amdgcn_mfma_f32_32x32x16_bf16(a1_, pk, o1, 0, 0, 0); } while (0)
; template <int MODE>
; __device__ __forceinline__ void attn_unit(LAS unsigned char* lds, const AttnArgs& A, int qb) {
;     ...
;         else if (MODE == M_MOBA) active = (i < 4) ? (key0 <= w0 + 31) : (((wmask >> ((i - 4) >> 2)) & 1ull) != 0ull);
;         else active = key0 <= w0 + 31;
;         if (active) {
;             f32x16 p0, p1;
; #pragma unroll
;             for (int r = 0; r < 16; ++r) { p0[r] = 0.f; p1[r] = 0.f; }
;             LAS unsigned char* kb = buf + kperm * 16 + hi * 1024;
; #pragma unroll
;             for (int d0 = 0; d0 < 4; ++d0) {
;                 const bf16x8 kf0 = *(const LAS bf16x8*)(kb + d0 * 2048), kf1 = *(const LAS bf16x8*)(kb + d0 * 2048 + 512);
;                 p0 = __builtin_amdgcn_mfma_f32_32x32x16_bf16(kf0, qr[d0], p0, 0, 0, 0);
;                 p1 = __builtin_amdgcn_mfma_f32_32x32x16_bf16(kf1, qr[d0], p1, 0, 0, 0);
;             }
;         if (prev_active) {
;             const LAS unsigned char* vb = lds + prevbuf + KB_BYTES + r32 * VT_STRIDE + hi * 16;
;     ...
;             PVS(0, pkP0); PVS(1, pkP1); PVS(2, pkP2); PVS(3, pkP3);
;     ...
;         }
.LBB0_997:
	s_add_i32 s80, s52, 0xffffff81
	s_cmp_le_i32 s80, s48
	s_cselect_b64 s[4:5], -1, 0
	s_cmp_gt_i32 s80, s48
	s_cbranch_scc1 .LBB0_1004
	v_add_u32_e32 v70, v186, v187
	s_andn2_b64 vcc, exec, s[26:27]
	ds_read_b128 v[66:69], v70 offset:17664
	ds_read_b128 v[74:77], v70 offset:19712
	ds_read_b128 v[78:81], v70 offset:18176
	ds_read_b128 v[82:85], v70 offset:20224
	ds_read_b128 v[86:89], v70 offset:21760
	ds_read_b128 v[90:93], v70 offset:22272
	ds_read_b128 v[94:97], v70 offset:23808
	ds_read_b128 v[206:209], v70 offset:24320
	s_waitcnt lgkmcnt(0)
	v_mfma_f32_32x32x16_bf16 v[34:49], v[66:69], v[98:101], 0
	v_mfma_f32_32x32x16_bf16 v[34:49], v[74:77], v[102:105], v[34:49]
	v_mfma_f32_32x32x16_bf16 v[50:65], v[78:81], v[98:101], 0
	v_mfma_f32_32x32x16_bf16 v[50:65], v[82:85], v[102:105], v[50:65]
	v_mfma_f32_32x32x16_bf16 v[34:49], v[86:89], v[106:109], v[34:49]
	v_mfma_f32_32x32x16_bf16 v[50:65], v[90:93], v[106:109], v[50:65]
	v_mfma_f32_32x32x16_bf16 v[34:49], v[94:97], v[110:113], v[34:49]
	v_mfma_f32_32x32x16_bf16 v[50:65], v[206:209], v[110:113], v[50:65]
	s_cbranch_vccnz .LBB0_1000
	ds_read_b128 v[66:69], v191 offset:8192
	ds_read_b128 v[74:77], v191 offset:12800
	ds_read_b128 v[78:81], v191 offset:8224
	ds_read_b128 v[82:85], v191 offset:12832
	ds_read_b128 v[86:89], v191 offset:8256
	ds_read_b128 v[90:93], v191 offset:12864
	ds_read_b128 v[94:97], v191 offset:8288
	ds_read_b128 v[206:209], v191 offset:12896
	s_waitcnt lgkmcnt(0)
	v_mfma_f32_32x32x16_bf16 v[2:17], v[66:69], v[150:153], v[2:17]
	v_mfma_f32_32x32x16_bf16 v[18:33], v[74:77], v[150:153], v[18:33]
	v_mfma_f32_32x32x16_bf16 v[2:17], v[78:81], v[142:145], v[2:17]
	v_mfma_f32_32x32x16_bf16 v[18:33], v[82:85], v[142:145], v[18:33]
	v_mfma_f32_32x32x16_bf16 v[2:17], v[86:89], v[146:149], v[2:17]
	v_mfma_f32_32x32x16_bf16 v[18:33], v[90:93], v[146:149], v[18:33]
	v_mfma_f32_32x32x16_bf16 v[2:17], v[94:97], v[138:141], v[2:17]
	v_mfma_f32_32x32x16_bf16 v[18:33], v[206:209], v[138:141], v[18:33]

; #define LAS __attribute__((address_space(3)))
; #define PVS(s, pk) do { const bf16x8 a0_ = *(const LAS bf16x8*)(vb + (s) * 32), a1_ = *(const LAS bf16x8*)(vb + 32 * VT_STRIDE + (s) * 32); \
;             o0 = __builtin_amdgcn_mfma_f32_32x32x16_bf16(a0_, pk, o0, 0, 0, 0); o1 = __builtin_amdgcn_mfma_f32_32x32x16_bf16(a1_, pk, o1, 0, 0, 0); } while (0)
; #define PVS(s, pk) do { const bf16x8 a0_ = *(const LAS bf16x8*)(vb + (s) * 32), a1_ = *(const LAS bf16x8*)(vb + 32 * VT_STRIDE + (s) * 32); \
;             o0 = __builtin_amdgcn_mfma_f32_32x32x16_bf16(a0_, pk, o0, 0, 0, 0); o1 = __builtin_amdgcn_mfma_f32_32x32x16_bf16(a1_, pk, o1, 0, 0, 0); } while (0)
; #define PVS(s, pk) do { const bf16x8 a0_ = *(const LAS bf16x8*)(vb + (s) * 32), a1_ = *(const LAS bf16x8*)(vb + 32 * VT_STRIDE + (s) * 32); \
;             o0 = __builtin_amdgcn_mfma_f32_32x32x16_bf16(a0_, pk, o0, 0, 0, 0); o1 = __builtin_amdgcn_mfma_f32_32x32x16_bf16(a1_, pk, o1, 0, 0, 0); } while (0)
; #define PVS(s, pk) do { const bf16x8 a0_ = *(const LAS bf16x8*)(vb + (s) * 32), a1_ = *(const LAS bf16x8*)(vb + 32 * VT_STRIDE + (s) * 32); \
;             o0 = __builtin_amdgcn_mfma_f32_32x32x16_bf16(a0_, pk, o0, 0, 0, 0); o1 = __builtin_amdgcn_mfma_f32_32x32x16_bf16(a1_, pk, o1, 0, 0, 0); } while (0)
; template <int MODE>
; __device__ __forceinline__ void attn_unit(LAS unsigned char* lds, const AttnArgs& A, int qb) {
;     ...
;         else if (MODE == M_MOBA) active = (i < 4) ? (key0 <= w0 + 31) : (((wmask >> ((i - 4) >> 2)) & 1ull) != 0ull);
;         else active = key0 <= w0 + 31;
;         if (active) {
;             f32x16 p0, p1;
; #pragma unroll
;             for (int r = 0; r < 16; ++r) { p0[r] = 0.f; p1[r] = 0.f; }
;             LAS unsigned char* kb = buf + kperm * 16 + hi * 1024;
; #pragma unroll
;             for (int d0 = 0; d0 < 4; ++d0) {
;                 const bf16x8 kf0 = *(const LAS bf16x8*)(kb + d0 * 2048), kf1 = *(const LAS bf16x8*)(kb + d0 * 2048 + 512);
;                 p0 = __builtin_amdgcn_mfma_f32_32x32x16_bf16(kf0, qr[d0], p0, 0, 0, 0);
;                 p1 = __builtin_amdgcn_mfma_f32_32x32x16_bf16(kf1, qr[d0], p1, 0, 0, 0);
;             }
;         if (prev_active) {
;             const LAS unsigned char* vb = lds + prevbuf + KB_BYTES + r32 * VT_STRIDE + hi * 16;
;     ...
;             PVS(0, pkP0); PVS(1, pkP1); PVS(2, pkP2); PVS(3, pkP3);
;     ...
;         }
.LBB0_1026:
	s_andn2_b64 vcc, exec, s[28:29]
	s_cbranch_vccnz .LBB0_1032
	v_add_u32_e32 v70, v186, v187
	s_nop 4
	s_nop 1
	s_and_b64 vcc, exec, s[10:11]
	ds_read_b128 v[66:69], v70 offset:35328
	ds_read_b128 v[74:77], v70 offset:37376
	ds_read_b128 v[78:81], v70 offset:35840
	ds_read_b128 v[82:85], v70 offset:37888
	ds_read_b128 v[86:89], v70 offset:39424
	ds_read_b128 v[90:93], v70 offset:39936
	ds_read_b128 v[94:97], v70 offset:41472
	ds_read_b128 v[206:209], v70 offset:41984
	s_waitcnt lgkmcnt(0)
	v_mfma_f32_32x32x16_bf16 v[34:49], v[66:69], v[98:101], 0
	v_mfma_f32_32x32x16_bf16 v[34:49], v[74:77], v[102:105], v[34:49]
	v_mfma_f32_32x32x16_bf16 v[50:65], v[78:81], v[98:101], 0
	v_mfma_f32_32x32x16_bf16 v[50:65], v[82:85], v[102:105], v[50:65]
	v_mfma_f32_32x32x16_bf16 v[34:49], v[86:89], v[106:109], v[34:49]
	v_mfma_f32_32x32x16_bf16 v[50:65], v[90:93], v[106:109], v[50:65]
	v_mfma_f32_32x32x16_bf16 v[34:49], v[94:97], v[110:113], v[34:49]
	v_mfma_f32_32x32x16_bf16 v[50:65], v[206:209], v[110:113], v[50:65]
	s_cbranch_vccnz .LBB0_1029
	v_add_u32_e32 v70, s2, v191
	ds_read_b128 v[66:69], v70 offset:8192
	ds_read_b128 v[74:77], v70 offset:12800
	ds_read_b128 v[78:81], v70 offset:8224
	ds_read_b128 v[82:85], v70 offset:12832
	ds_read_b128 v[86:89], v70 offset:8256
	ds_read_b128 v[90:93], v70 offset:12864
	ds_read_b128 v[94:97], v70 offset:8288
	ds_read_b128 v[206:209], v70 offset:12896
	s_waitcnt lgkmcnt(0)
	v_mfma_f32_32x32x16_bf16 v[2:17], v[66:69], v[150:153], v[2:17]
	v_mfma_f32_32x32x16_bf16 v[18:33], v[74:77], v[150:153], v[18:33]
	v_mfma_f32_32x32x16_bf16 v[2:17], v[78:81], v[142:145], v[2:17]
	v_mfma_f32_32x32x16_bf16 v[18:33], v[82:85], v[142:145], v[18:33]
	v_mfma_f32_32x32x16_bf16 v[2:17], v[86:89], v[146:149], v[2:17]
	v_mfma_f32_32x32x16_bf16 v[18:33], v[90:93], v[146:149], v[18:33]
	v_mfma_f32_32x32x16_bf16 v[2:17], v[94:97], v[138:141], v[2:17]
	v_mfma_f32_32x32x16_bf16 v[18:33], v[206:209], v[138:141], v[18:33]

; __device__ __forceinline__ void store4(bf16_t* p, f32x4 v) { u32x2 w; w.x = cvt_pk_bf16(v[0], v[1]); w.y = cvt_pk_bf16(v[2], v[3]); *(u32x2*)p = w; }
; __device__ __forceinline__ float rstd_of(const float* ssq, int row) { return rsqrtf(ssq[row] * (1.0f / 1024.0f) + 1e-6f); }
;     __device__ __forceinline__ void operator()(const f32x4 (&acc)[2][2][4][2], const Unit& u, int wr, int wc, int fr, int fq) const {
;         const int g0 = 252 * u.pm - 2 + 126 * wr + fr;
;         float rs[8];
; #pragma unroll
;         for (int q = 0; q < 8; ++q) { int r = g0 + 16 * q; r = r < 0 ? 0 : (r > SEQ - 1 ? SEQ - 1 : r); rs[q] = rstd_of(ssq, r); }
; #pragma unroll
;         for (int n = 0; n < 2; ++n) {
;             const int col = 128 * u.pn + 32 * wc + 8 * fq + 4 * n;
;             const f32x4 wg0 = *(const f32x4*)(cw + col), wg1 = *(const f32x4*)(cw + 5632 + col), wg2 = *(const f32x4*)(cw + 2 * 5632 + col), bg = *(const f32x4*)(cb + col);
;             const f32x4 wv0 = *(const f32x4*)(cw + 2816 + col), wv1 = *(const f32x4*)(cw + 5632 + 2816 + col), wv2 = *(const f32x4*)(cw + 2 * 5632 + 2816 + col), bv = *(const f32x4*)(cb + 2816 + col);
;             f32x4 pg = (f32x4){0.f, 0.f, 0.f, 0.f}, pv = (f32x4){0.f, 0.f, 0.f, 0.f};
; #pragma unroll
;             for (int q = 0; q < 8; ++q) {
;                 const f32x4 ug = acc[q >> 2][0][q & 3][n] * rs[q], uv = acc[q >> 2][1][q & 3][n] * rs[q];
;                 f32x4 res;
; #pragma unroll
;                 for (int j = 0; j < 4; ++j) {
;                     const float ga1 = dpp_ror1(ug[j]), gb1 = dpp_ror1(pg[j]), ga2 = dpp_ror2(ug[j]), gb2 = dpp_ror2(pg[j]);
;                     const float va1 = dpp_ror1(uv[j]), vb1 = dpp_ror1(pv[j]), va2 = dpp_ror2(uv[j]), vb2 = dpp_ror2(pv[j]);
;                     const float g1 = fr >= 1 ? ga1 : gb1, g2 = fr >= 2 ? ga2 : gb2, v1 = fr >= 1 ? va1 : vb1, v2 = fr >= 2 ? va2 : vb2;
;                     const float cgv = bg[j] + wg0[j] * g2 + wg1[j] * g1 + wg2[j] * ug[j];
;                     const float cvv = bv[j] + wv0[j] * v2 + wv1[j] * v1 + wv2[j] * uv[j];
;                     res[j] = cgv * __builtin_amdgcn_rcpf(1.0f + __builtin_amdgcn_exp2f(-1.44269504f * cgv)) * cvv;
;                 }
;                 pg = ug; pv = uv;
;                 const int row = g0 + 16 * q;
;                 if ((q > 0 || fr >= 2) && row < SEQ) store4(ACT + (size_t)row * 2816 + col, res);
.LBB0_2323:
	s_mulk_i32 s0, 0xfc
	v_add_u32_e32 v230, s0, v210
	s_movk_i32 s12, 0x3fff
	v_med3_i32 v234, v230, 0, s12
	v_lshlrev_b32_e32 v234, 2, v234
	global_load_dword v172, v234, s[28:29]
	v_add_u32_e32 v235, 16, v230
	v_med3_i32 v235, v235, 0, s12
	v_lshlrev_b32_e32 v235, 2, v235
	global_load_dword v173, v235, s[28:29]
	v_add_u32_e32 v236, 32, v230
	v_med3_i32 v236, v236, 0, s12
	v_lshlrev_b32_e32 v236, 2, v236
	global_load_dword v174, v236, s[28:29]
	v_add_u32_e32 v237, 48, v230
	v_med3_i32 v237, v237, 0, s12
	v_lshlrev_b32_e32 v237, 2, v237
	global_load_dword v175, v237, s[28:29]
	v_add_u32_e32 v238, 64, v230
	v_med3_i32 v238, v238, 0, s12
	v_lshlrev_b32_e32 v238, 2, v238
	global_load_dword v176, v238, s[28:29]
	v_add_u32_e32 v239, 80, v230
	v_med3_i32 v239, v239, 0, s12
	v_lshlrev_b32_e32 v239, 2, v239
	global_load_dword v177, v239, s[28:29]
	v_add_u32_e32 v240, 96, v230
	v_med3_i32 v240, v240, 0, s12
	v_lshlrev_b32_e32 v240, 2, v240
	global_load_dword v178, v240, s[28:29]
	v_add_u32_e32 v241, 112, v230
	v_med3_i32 v241, v241, 0, s12
	v_lshlrev_b32_e32 v241, 2, v241
	global_load_dword v179, v241, s[28:29]
	v_lshl_or_b32 v231, s4, 7, v211
	v_lshlrev_b32_e32 v232, 2, v231
	global_load_dwordx4 v[82:85], v232, s[30:31]
	global_load_dwordx4 v[86:89], v232, s[38:39]
	global_load_dwordx4 v[90:93], v232, s[40:41]
	global_load_dwordx4 v[94:97], v232, s[34:35]
	global_load_dwordx4 v[98:101], v232, s[42:43]
	global_load_dwordx4 v[102:105], v232, s[44:45]
	global_load_dwordx4 v[106:109], v232, s[46:47]
	global_load_dwordx4 v[110:113], v232, s[48:49]
	v_lshlrev_b32_e32 v231, 1, v231
	v_mad_i32_i24 v233, v230, s87, v231
	s_waitcnt vmcnt(8)
	v_fmamk_f32 v172, v172, 0x3a800000, v217
	v_fmamk_f32 v173, v173, 0x3a800000, v217
	v_fmamk_f32 v174, v174, 0x3a800000, v217
	v_fmamk_f32 v175, v175, 0x3a800000, v217
	v_fmamk_f32 v176, v176, 0x3a800000, v217
	v_fmamk_f32 v177, v177, 0x3a800000, v217
	v_fmamk_f32 v178, v178, 0x3a800000, v217
	v_fmamk_f32 v179, v179, 0x3a800000, v217
	v_rsq_f32_e32 v172, v172
	v_rsq_f32_e32 v173, v173
	v_rsq_f32_e32 v174, v174
	v_rsq_f32_e32 v175, v175
	v_rsq_f32_e32 v176, v176
	v_rsq_f32_e32 v177, v177
	v_rsq_f32_e32 v178, v178
	v_rsq_f32_e32 v179, v179
	s_waitcnt vmcnt(0)
	s_mov_b32 s12, 0xbfb8aa3b
	v_pk_mul_f32 v[158:159], v[158:159], v[172:173] op_sel_hi:[1,0]
	v_pk_mul_f32 v[160:161], v[160:161], v[172:173] op_sel_hi:[1,0]
	v_pk_mul_f32 v[154:155], v[154:155], v[172:173] op_sel_hi:[1,0]
	v_pk_mul_f32 v[156:157], v[156:157], v[172:173] op_sel_hi:[1,0]
	v_pk_mov_b32 v[180:181], v[94:95], v[94:95] op_sel:[0,1]
	v_pk_mov_b32 v[182:183], v[96:97], v[96:97] op_sel:[0,1]
	v_pk_mov_b32 v[184:185], v[110:111], v[110:111] op_sel:[0,1]
	v_pk_mov_b32 v[186:187], v[112:113], v[112:113] op_sel:[0,1]
	v_fmac_f32_dpp v180, v158, v82 row_shr:2 row_mask:0xf bank_mask:0xf
	v_fmac_f32_dpp v181, v159, v83 row_shr:2 row_mask:0xf bank_mask:0xf
	v_fmac_f32_dpp v182, v160, v84 row_shr:2 row_mask:0xf bank_mask:0xf
	v_fmac_f32_dpp v183, v161, v85 row_shr:2 row_mask:0xf bank_mask:0xf
	v_fmac_f32_dpp v184, v154, v98 row_shr:2 row_mask:0xf bank_mask:0xf
	v_fmac_f32_dpp v185, v155, v99 row_shr:2 row_mask:0xf bank_mask:0xf
	v_fmac_f32_dpp v186, v156, v100 row_shr:2 row_mask:0xf bank_mask:0xf
	v_fmac_f32_dpp v187, v157, v101 row_shr:2 row_mask:0xf bank_mask:0xf
	v_fmac_f32_dpp v180, v158, v86 row_shr:1 row_mask:0xf bank_mask:0xf
	v_fmac_f32_dpp v181, v159, v87 row_shr:1 row_mask:0xf bank_mask:0xf
	v_fmac_f32_dpp v182, v160, v88 row_shr:1 row_mask:0xf bank_mask:0xf
	v_fmac_f32_dpp v183, v161, v89 row_shr:1 row_mask:0xf bank_mask:0xf
	v_fmac_f32_dpp v184, v154, v102 row_shr:1 row_mask:0xf bank_mask:0xf
	v_fmac_f32_dpp v185, v155, v103 row_shr:1 row_mask:0xf bank_mask:0xf
	v_fmac_f32_dpp v186, v156, v104 row_shr:1 row_mask:0xf bank_mask:0xf
	v_fmac_f32_dpp v187, v157, v105 row_shr:1 row_mask:0xf bank_mask:0xf
	v_pk_fma_f32 v[180:181], v[158:159], v[90:91], v[180:181]
	v_pk_fma_f32 v[182:183], v[160:161], v[92:93], v[182:183]
	v_pk_fma_f32 v[184:185], v[154:155], v[106:107], v[184:185]
	v_pk_fma_f32 v[186:187], v[156:157], v[108:109], v[186:187]
	v_pk_mul_f32 v[188:189], v[180:181], s[12:13] op_sel_hi:[1,0]
	v_pk_mul_f32 v[190:191], v[182:183], s[12:13] op_sel_hi:[1,0]
	v_exp_f32_e32 v188, v188
	v_exp_f32_e32 v189, v189
	v_exp_f32_e32 v190, v190
	v_exp_f32_e32 v191, v191
	v_pk_add_f32 v[188:189], v[188:189], 1.0 op_sel_hi:[1,0]
	v_pk_add_f32 v[190:191], v[190:191], 1.0 op_sel_hi:[1,0]
	v_rcp_f32_e32 v188, v188
	v_rcp_f32_e32 v189, v189
	v_rcp_f32_e32 v190, v190
	v_rcp_f32_e32 v191, v191
	v_cmp_gt_i32_e32 vcc, 0x4000, v230
	v_pk_mul_f32 v[188:189], v[180:181], v[188:189]
	v_pk_mul_f32 v[190:191], v[182:183], v[190:191]
	v_pk_mul_f32 v[188:189], v[184:185], v[188:189]
	v_pk_mul_f32 v[190:191], v[186:187], v[190:191]
	s_and_b64 vcc, vcc, s[8:9]
	v_cvt_pk_bf16_f32 v206, v188, v189
	v_cvt_pk_bf16_f32 v207, v190, v191
	s_and_saveexec_b64 s[4:5], vcc
	s_cbranch_execz .Lupepi_skip0
	global_store_dwordx2 v233, v[206:207], s[26:27]
; __device__ __forceinline__ void store4(bf16_t* p, f32x4 v) { u32x2 w; w.x = cvt_pk_bf16(v[0], v[1]); w.y = cvt_pk_bf16(v[2], v[3]); *(u32x2*)p = w; }
; __device__ __forceinline__ float dpp_ror1(float x) { float r; asm volatile("s_nop 1\n\tv_mov_b32_dpp %0, %1 row_ror:1 row_mask:0xf bank_mask:0xf" : "=v"(r) : "v"(x)); return r; }
; __device__ __forceinline__ float dpp_ror2(float x) { float r; asm volatile("s_nop 1\n\tv_mov_b32_dpp %0, %1 row_ror:2 row_mask:0xf bank_mask:0xf" : "=v"(r) : "v"(x)); return r; }
;     __device__ __forceinline__ void operator()(const f32x4 (&acc)[2][2][4][2], const Unit& u, int wr, int wc, int fr, int fq) const {
;     ...
; #pragma unroll
;             for (int q = 0; q < 8; ++q) {
;                 const f32x4 ug = acc[q >> 2][0][q & 3][n] * rs[q], uv = acc[q >> 2][1][q & 3][n] * rs[q];
;                 f32x4 res;
; #pragma unroll
;                 for (int j = 0; j < 4; ++j) {
;                     const float ga1 = dpp_ror1(ug[j]), gb1 = dpp_ror1(pg[j]), ga2 = dpp_ror2(ug[j]), gb2 = dpp_ror2(pg[j]);
;                     const float va1 = dpp_ror1(uv[j]), vb1 = dpp_ror1(pv[j]), va2 = dpp_ror2(uv[j]), vb2 = dpp_ror2(pv[j]);
;                     const float g1 = fr >= 1 ? ga1 : gb1, g2 = fr >= 2 ? ga2 : gb2, v1 = fr >= 1 ? va1 : vb1, v2 = fr >= 2 ? va2 : vb2;
;                     const float cgv = bg[j] + wg0[j] * g2 + wg1[j] * g1 + wg2[j] * ug[j];
;                     const float cvv = bv[j] + wv0[j] * v2 + wv1[j] * v1 + wv2[j] * uv[j];
;                     res[j] = cgv * __builtin_amdgcn_rcpf(1.0f + __builtin_amdgcn_exp2f(-1.44269504f * cgv)) * cvv;
;                 }
;                 pg = ug; pv = uv;
;                 const int row = g0 + 16 * q;
;                 if ((q > 0 || fr >= 2) && row < SEQ) store4(ACT + (size_t)row * 2816 + col, res);
.Lupepi_skip0:
	s_or_b64 exec, exec, s[4:5]
	v_pk_mul_f32 v[150:151], v[150:151], v[172:173] op_sel:[0,1] op_sel_hi:[1,1]
	v_pk_mul_f32 v[152:153], v[152:153], v[172:173] op_sel:[0,1] op_sel_hi:[1,1]
	v_pk_mul_f32 v[146:147], v[146:147], v[172:173] op_sel:[0,1] op_sel_hi:[1,1]
	v_pk_mul_f32 v[148:149], v[148:149], v[172:173] op_sel:[0,1] op_sel_hi:[1,1]
	v_pk_mov_b32 v[180:181], v[94:95], v[94:95] op_sel:[0,1]
	v_pk_mov_b32 v[182:183], v[96:97], v[96:97] op_sel:[0,1]
	v_pk_mov_b32 v[184:185], v[110:111], v[110:111] op_sel:[0,1]
	v_pk_mov_b32 v[186:187], v[112:113], v[112:113] op_sel:[0,1]
	v_fmac_f32_dpp v180, v150, v82 row_shr:2 row_mask:0xf bank_mask:0xf
	v_fmac_f32_dpp v181, v151, v83 row_shr:2 row_mask:0xf bank_mask:0xf
	v_fmac_f32_dpp v182, v152, v84 row_shr:2 row_mask:0xf bank_mask:0xf
	v_fmac_f32_dpp v183, v153, v85 row_shr:2 row_mask:0xf bank_mask:0xf
	v_fmac_f32_dpp v184, v146, v98 row_shr:2 row_mask:0xf bank_mask:0xf
	v_fmac_f32_dpp v185, v147, v99 row_shr:2 row_mask:0xf bank_mask:0xf
	v_fmac_f32_dpp v186, v148, v100 row_shr:2 row_mask:0xf bank_mask:0xf
	v_fmac_f32_dpp v187, v149, v101 row_shr:2 row_mask:0xf bank_mask:0xf
	v_fmac_f32_dpp v180, v158, v82 row_shl:14 row_mask:0xf bank_mask:0xf
	v_fmac_f32_dpp v181, v159, v83 row_shl:14 row_mask:0xf bank_mask:0xf
	v_fmac_f32_dpp v182, v160, v84 row_shl:14 row_mask:0xf bank_mask:0xf
	v_fmac_f32_dpp v183, v161, v85 row_shl:14 row_mask:0xf bank_mask:0xf
	v_fmac_f32_dpp v184, v154, v98 row_shl:14 row_mask:0xf bank_mask:0xf
	v_fmac_f32_dpp v185, v155, v99 row_shl:14 row_mask:0xf bank_mask:0xf
	v_fmac_f32_dpp v186, v156, v100 row_shl:14 row_mask:0xf bank_mask:0xf
	v_fmac_f32_dpp v187, v157, v101 row_shl:14 row_mask:0xf bank_mask:0xf
	v_fmac_f32_dpp v180, v150, v86 row_shr:1 row_mask:0xf bank_mask:0xf
	v_fmac_f32_dpp v181, v151, v87 row_shr:1 row_mask:0xf bank_mask:0xf
	v_fmac_f32_dpp v182, v152, v88 row_shr:1 row_mask:0xf bank_mask:0xf
	v_fmac_f32_dpp v183, v153, v89 row_shr:1 row_mask:0xf bank_mask:0xf
	v_fmac_f32_dpp v184, v146, v102 row_shr:1 row_mask:0xf bank_mask:0xf
	v_fmac_f32_dpp v185, v147, v103 row_shr:1 row_mask:0xf bank_mask:0xf
	v_fmac_f32_dpp v186, v148, v104 row_shr:1 row_mask:0xf bank_mask:0xf
	v_fmac_f32_dpp v187, v149, v105 row_shr:1 row_mask:0xf bank_mask:0xf
	v_fmac_f32_dpp v180, v158, v86 row_shl:15 row_mask:0xf bank_mask:0xf
	v_fmac_f32_dpp v181, v159, v87 row_shl:15 row_mask:0xf bank_mask:0xf
	v_fmac_f32_dpp v182, v160, v88 row_shl:15 row_mask:0xf bank_mask:0xf
	v_fmac_f32_dpp v183, v161, v89 row_shl:15 row_mask:0xf bank_mask:0xf
	v_fmac_f32_dpp v184, v154, v102 row_shl:15 row_mask:0xf bank_mask:0xf
	v_fmac_f32_dpp v185, v155, v103 row_shl:15 row_mask:0xf bank_mask:0xf
	v_fmac_f32_dpp v186, v156, v104 row_shl:15 row_mask:0xf bank_mask:0xf
	v_fmac_f32_dpp v187, v157, v105 row_shl:15 row_mask:0xf bank_mask:0xf
	v_pk_fma_f32 v[180:181], v[150:151], v[90:91], v[180:181]
	v_pk_fma_f32 v[182:183], v[152:153], v[92:93], v[182:183]
	v_pk_fma_f32 v[184:185], v[146:147], v[106:107], v[184:185]
	v_pk_fma_f32 v[186:187], v[148:149], v[108:109], v[186:187]
	v_pk_mul_f32 v[188:189], v[180:181], s[12:13] op_sel_hi:[1,0]
	v_pk_mul_f32 v[190:191], v[182:183], s[12:13] op_sel_hi:[1,0]
	v_exp_f32_e32 v188, v188
	v_exp_f32_e32 v189, v189
	v_exp_f32_e32 v190, v190
	v_exp_f32_e32 v191, v191
	v_pk_add_f32 v[188:189], v[188:189], 1.0 op_sel_hi:[1,0]
	v_pk_add_f32 v[190:191], v[190:191], 1.0 op_sel_hi:[1,0]
	v_rcp_f32_e32 v188, v188
	v_rcp_f32_e32 v189, v189
	v_rcp_f32_e32 v190, v190
	v_rcp_f32_e32 v191, v191
	v_cmp_gt_i32_e32 vcc, 0x3ff0, v230
	v_pk_mul_f32 v[188:189], v[180:181], v[188:189]
	v_pk_mul_f32 v[190:191], v[182:183], v[190:191]
	v_pk_mul_f32 v[188:189], v[184:185], v[188:189]
	v_pk_mul_f32 v[190:191], v[186:187], v[190:191]
	v_add_u32_e32 v234, 0x16000, v233
	v_cvt_pk_bf16_f32 v208, v188, v189
	v_cvt_pk_bf16_f32 v209, v190, v191
	s_and_saveexec_b64 s[4:5], vcc
	s_cbranch_execz .Lupepi_skip1
	global_store_dwordx2 v234, v[208:209], s[26:27]
.Lupepi_skip1:
	s_or_b64 exec, exec, s[4:5]
	v_pk_mul_f32 v[142:143], v[142:143], v[174:175] op_sel_hi:[1,0]
	v_pk_mul_f32 v[144:145], v[144:145], v[174:175] op_sel_hi:[1,0]
	v_pk_mul_f32 v[138:139], v[138:139], v[174:175] op_sel_hi:[1,0]
	v_pk_mul_f32 v[140:141], v[140:141], v[174:175] op_sel_hi:[1,0]
	v_pk_mov_b32 v[180:181], v[94:95], v[94:95] op_sel:[0,1]
	v_pk_mov_b32 v[182:183], v[96:97], v[96:97] op_sel:[0,1]
	v_pk_mov_b32 v[184:185], v[110:111], v[110:111] op_sel:[0,1]
	v_pk_mov_b32 v[186:187], v[112:113], v[112:113] op_sel:[0,1]
	v_fmac_f32_dpp v180, v142, v82 row_shr:2 row_mask:0xf bank_mask:0xf
	v_fmac_f32_dpp v181, v143, v83 row_shr:2 row_mask:0xf bank_mask:0xf
	v_fmac_f32_dpp v182, v144, v84 row_shr:2 row_mask:0xf bank_mask:0xf
	v_fmac_f32_dpp v183, v145, v85 row_shr:2 row_mask:0xf bank_mask:0xf
	v_fmac_f32_dpp v184, v138, v98 row_shr:2 row_mask:0xf bank_mask:0xf
	v_fmac_f32_dpp v185, v139, v99 row_shr:2 row_mask:0xf bank_mask:0xf
	v_fmac_f32_dpp v186, v140, v100 row_shr:2 row_mask:0xf bank_mask:0xf
	v_fmac_f32_dpp v187, v141, v101 row_shr:2 row_mask:0xf bank_mask:0xf
	v_fmac_f32_dpp v180, v150, v82 row_shl:14 row_mask:0xf bank_mask:0xf
	v_fmac_f32_dpp v181, v151, v83 row_shl:14 row_mask:0xf bank_mask:0xf
	v_fmac_f32_dpp v182, v152, v84 row_shl:14 row_mask:0xf bank_mask:0xf
	v_fmac_f32_dpp v183, v153, v85 row_shl:14 row_mask:0xf bank_mask:0xf
	v_fmac_f32_dpp v184, v146, v98 row_shl:14 row_mask:0xf bank_mask:0xf
	v_fmac_f32_dpp v185, v147, v99 row_shl:14 row_mask:0xf bank_mask:0xf
	v_fmac_f32_dpp v186, v148, v100 row_shl:14 row_mask:0xf bank_mask:0xf
	v_fmac_f32_dpp v187, v149, v101 row_shl:14 row_mask:0xf bank_mask:0xf
; __device__ __forceinline__ void store4(bf16_t* p, f32x4 v) { u32x2 w; w.x = cvt_pk_bf16(v[0], v[1]); w.y = cvt_pk_bf16(v[2], v[3]); *(u32x2*)p = w; }
; __device__ __forceinline__ float dpp_ror1(float x) { float r; asm volatile("s_nop 1\n\tv_mov_b32_dpp %0, %1 row_ror:1 row_mask:0xf bank_mask:0xf" : "=v"(r) : "v"(x)); return r; }
; __device__ __forceinline__ float dpp_ror2(float x) { float r; asm volatile("s_nop 1\n\tv_mov_b32_dpp %0, %1 row_ror:2 row_mask:0xf bank_mask:0xf" : "=v"(r) : "v"(x)); return r; }
;     __device__ __forceinline__ void operator()(const f32x4 (&acc)[2][2][4][2], const Unit& u, int wr, int wc, int fr, int fq) const {
;     ...
; #pragma unroll
;             for (int q = 0; q < 8; ++q) {
;                 const f32x4 ug = acc[q >> 2][0][q & 3][n] * rs[q], uv = acc[q >> 2][1][q & 3][n] * rs[q];
;                 f32x4 res;
; #pragma unroll
;                 for (int j = 0; j < 4; ++j) {
;                     const float ga1 = dpp_ror1(ug[j]), gb1 = dpp_ror1(pg[j]), ga2 = dpp_ror2(ug[j]), gb2 = dpp_ror2(pg[j]);
;                     const float va1 = dpp_ror1(uv[j]), vb1 = dpp_ror1(pv[j]), va2 = dpp_ror2(uv[j]), vb2 = dpp_ror2(pv[j]);
;                     const float g1 = fr >= 1 ? ga1 : gb1, g2 = fr >= 2 ? ga2 : gb2, v1 = fr >= 1 ? va1 : vb1, v2 = fr >= 2 ? va2 : vb2;
;                     const float cgv = bg[j] + wg0[j] * g2 + wg1[j] * g1 + wg2[j] * ug[j];
;                     const float cvv = bv[j] + wv0[j] * v2 + wv1[j] * v1 + wv2[j] * uv[j];
;                     res[j] = cgv * __builtin_amdgcn_rcpf(1.0f + __builtin_amdgcn_exp2f(-1.44269504f * cgv)) * cvv;
;                 }
;                 pg = ug; pv = uv;
;                 const int row = g0 + 16 * q;
;                 if ((q > 0 || fr >= 2) && row < SEQ) store4(ACT + (size_t)row * 2816 + col, res);
	v_fmac_f32_dpp v180, v142, v86 row_shr:1 row_mask:0xf bank_mask:0xf
	v_fmac_f32_dpp v181, v143, v87 row_shr:1 row_mask:0xf bank_mask:0xf
	v_fmac_f32_dpp v182, v144, v88 row_shr:1 row_mask:0xf bank_mask:0xf
	v_fmac_f32_dpp v183, v145, v89 row_shr:1 row_mask:0xf bank_mask:0xf
	v_fmac_f32_dpp v184, v138, v102 row_shr:1 row_mask:0xf bank_mask:0xf
	v_fmac_f32_dpp v185, v139, v103 row_shr:1 row_mask:0xf bank_mask:0xf
	v_fmac_f32_dpp v186, v140, v104 row_shr:1 row_mask:0xf bank_mask:0xf
	v_fmac_f32_dpp v187, v141, v105 row_shr:1 row_mask:0xf bank_mask:0xf
	v_fmac_f32_dpp v180, v150, v86 row_shl:15 row_mask:0xf bank_mask:0xf
	v_fmac_f32_dpp v181, v151, v87 row_shl:15 row_mask:0xf bank_mask:0xf
	v_fmac_f32_dpp v182, v152, v88 row_shl:15 row_mask:0xf bank_mask:0xf
	v_fmac_f32_dpp v183, v153, v89 row_shl:15 row_mask:0xf bank_mask:0xf
	v_fmac_f32_dpp v184, v146, v102 row_shl:15 row_mask:0xf bank_mask:0xf
	v_fmac_f32_dpp v185, v147, v103 row_shl:15 row_mask:0xf bank_mask:0xf
	v_fmac_f32_dpp v186, v148, v104 row_shl:15 row_mask:0xf bank_mask:0xf
	v_fmac_f32_dpp v187, v149, v105 row_shl:15 row_mask:0xf bank_mask:0xf
	v_pk_fma_f32 v[180:181], v[142:143], v[90:91], v[180:181]
	v_pk_fma_f32 v[182:183], v[144:145], v[92:93], v[182:183]
	v_pk_fma_f32 v[184:185], v[138:139], v[106:107], v[184:185]
	v_pk_fma_f32 v[186:187], v[140:141], v[108:109], v[186:187]
	v_pk_mul_f32 v[188:189], v[180:181], s[12:13] op_sel_hi:[1,0]
	v_pk_mul_f32 v[190:191], v[182:183], s[12:13] op_sel_hi:[1,0]
	v_exp_f32_e32 v188, v188
	v_exp_f32_e32 v189, v189
	v_exp_f32_e32 v190, v190
	v_exp_f32_e32 v191, v191
	v_pk_add_f32 v[188:189], v[188:189], 1.0 op_sel_hi:[1,0]
	v_pk_add_f32 v[190:191], v[190:191], 1.0 op_sel_hi:[1,0]
	v_rcp_f32_e32 v188, v188
	v_rcp_f32_e32 v189, v189
	v_rcp_f32_e32 v190, v190
	v_rcp_f32_e32 v191, v191
	v_cmp_gt_i32_e32 vcc, 0x3fe0, v230
	v_pk_mul_f32 v[188:189], v[180:181], v[188:189]
	v_pk_mul_f32 v[190:191], v[182:183], v[190:191]
	v_pk_mul_f32 v[188:189], v[184:185], v[188:189]
	v_pk_mul_f32 v[190:191], v[186:187], v[190:191]
	v_add_u32_e32 v234, 0x2c000, v233
	v_cvt_pk_bf16_f32 v206, v188, v189
	v_cvt_pk_bf16_f32 v207, v190, v191
	s_and_saveexec_b64 s[4:5], vcc
	s_cbranch_execz .Lupepi_skip2
	global_store_dwordx2 v234, v[206:207], s[26:27]
.Lupepi_skip2:
	s_or_b64 exec, exec, s[4:5]
	v_pk_mul_f32 v[134:135], v[134:135], v[174:175] op_sel:[0,1] op_sel_hi:[1,1]
	v_pk_mul_f32 v[136:137], v[136:137], v[174:175] op_sel:[0,1] op_sel_hi:[1,1]
	v_pk_mul_f32 v[130:131], v[130:131], v[174:175] op_sel:[0,1] op_sel_hi:[1,1]
	v_pk_mul_f32 v[132:133], v[132:133], v[174:175] op_sel:[0,1] op_sel_hi:[1,1]
	v_pk_mov_b32 v[180:181], v[94:95], v[94:95] op_sel:[0,1]
	v_pk_mov_b32 v[182:183], v[96:97], v[96:97] op_sel:[0,1]
	v_pk_mov_b32 v[184:185], v[110:111], v[110:111] op_sel:[0,1]
	v_pk_mov_b32 v[186:187], v[112:113], v[112:113] op_sel:[0,1]
	v_fmac_f32_dpp v180, v134, v82 row_shr:2 row_mask:0xf bank_mask:0xf
	v_fmac_f32_dpp v181, v135, v83 row_shr:2 row_mask:0xf bank_mask:0xf
	v_fmac_f32_dpp v182, v136, v84 row_shr:2 row_mask:0xf bank_mask:0xf
	v_fmac_f32_dpp v183, v137, v85 row_shr:2 row_mask:0xf bank_mask:0xf
	v_fmac_f32_dpp v184, v130, v98 row_shr:2 row_mask:0xf bank_mask:0xf
	v_fmac_f32_dpp v185, v131, v99 row_shr:2 row_mask:0xf bank_mask:0xf
	v_fmac_f32_dpp v186, v132, v100 row_shr:2 row_mask:0xf bank_mask:0xf
	v_fmac_f32_dpp v187, v133, v101 row_shr:2 row_mask:0xf bank_mask:0xf
	v_fmac_f32_dpp v180, v142, v82 row_shl:14 row_mask:0xf bank_mask:0xf
	v_fmac_f32_dpp v181, v143, v83 row_shl:14 row_mask:0xf bank_mask:0xf
	v_fmac_f32_dpp v182, v144, v84 row_shl:14 row_mask:0xf bank_mask:0xf
	v_fmac_f32_dpp v183, v145, v85 row_shl:14 row_mask:0xf bank_mask:0xf
	v_fmac_f32_dpp v184, v138, v98 row_shl:14 row_mask:0xf bank_mask:0xf
	v_fmac_f32_dpp v185, v139, v99 row_shl:14 row_mask:0xf bank_mask:0xf
	v_fmac_f32_dpp v186, v140, v100 row_shl:14 row_mask:0xf bank_mask:0xf
	v_fmac_f32_dpp v187, v141, v101 row_shl:14 row_mask:0xf bank_mask:0xf
	v_fmac_f32_dpp v180, v134, v86 row_shr:1 row_mask:0xf bank_mask:0xf
	v_fmac_f32_dpp v181, v135, v87 row_shr:1 row_mask:0xf bank_mask:0xf
	v_fmac_f32_dpp v182, v136, v88 row_shr:1 row_mask:0xf bank_mask:0xf
	v_fmac_f32_dpp v183, v137, v89 row_shr:1 row_mask:0xf bank_mask:0xf
	v_fmac_f32_dpp v184, v130, v102 row_shr:1 row_mask:0xf bank_mask:0xf
	v_fmac_f32_dpp v185, v131, v103 row_shr:1 row_mask:0xf bank_mask:0xf
	v_fmac_f32_dpp v186, v132, v104 row_shr:1 row_mask:0xf bank_mask:0xf
	v_fmac_f32_dpp v187, v133, v105 row_shr:1 row_mask:0xf bank_mask:0xf
	v_fmac_f32_dpp v180, v142, v86 row_shl:15 row_mask:0xf bank_mask:0xf
	v_fmac_f32_dpp v181, v143, v87 row_shl:15 row_mask:0xf bank_mask:0xf
	v_fmac_f32_dpp v182, v144, v88 row_shl:15 row_mask:0xf bank_mask:0xf
	v_fmac_f32_dpp v183, v145, v89 row_shl:15 row_mask:0xf bank_mask:0xf
	v_fmac_f32_dpp v184, v138, v102 row_shl:15 row_mask:0xf bank_mask:0xf
	v_fmac_f32_dpp v185, v139, v103 row_shl:15 row_mask:0xf bank_mask:0xf
	v_fmac_f32_dpp v186, v140, v104 row_shl:15 row_mask:0xf bank_mask:0xf
	v_fmac_f32_dpp v187, v141, v105 row_shl:15 row_mask:0xf bank_mask:0xf
	v_pk_fma_f32 v[180:181], v[134:135], v[90:91], v[180:181]
	v_pk_fma_f32 v[182:183], v[136:137], v[92:93], v[182:183]
	v_pk_fma_f32 v[184:185], v[130:131], v[106:107], v[184:185]
	v_pk_fma_f32 v[186:187], v[132:133], v[108:109], v[186:187]
	v_pk_mul_f32 v[188:189], v[180:181], s[12:13] op_sel_hi:[1,0]
	v_pk_mul_f32 v[190:191], v[182:183], s[12:13] op_sel_hi:[1,0]
	v_exp_f32_e32 v188, v188
	v_exp_f32_e32 v189, v189
	v_exp_f32_e32 v190, v190
	v_exp_f32_e32 v191, v191
	v_pk_add_f32 v[188:189], v[188:189], 1.0 op_sel_hi:[1,0]
	v_pk_add_f32 v[190:191], v[190:191], 1.0 op_sel_hi:[1,0]
	v_rcp_f32_e32 v188, v188
	v_rcp_f32_e32 v189, v189
	v_rcp_f32_e32 v190, v190
	v_rcp_f32_e32 v191, v191
	v_cmp_gt_i32_e32 vcc, 0x3fd0, v230
	v_pk_mul_f32 v[188:189], v[180:181], v[188:189]
	v_pk_mul_f32 v[190:191], v[182:183], v[190:191]
	v_pk_mul_f32 v[188:189], v[184:185], v[188:189]
	v_pk_mul_f32 v[190:191], v[186:187], v[190:191]
	v_add_u32_e32 v234, 0x42000, v233
	v_cvt_pk_bf16_f32 v208, v188, v189
	v_cvt_pk_bf16_f32 v209, v190, v191
	s_and_saveexec_b64 s[4:5], vcc
	s_cbranch_execz .Lupepi_skip3
	global_store_dwordx2 v234, v[208:209], s[26:27]
; __device__ __forceinline__ void store4(bf16_t* p, f32x4 v) { u32x2 w; w.x = cvt_pk_bf16(v[0], v[1]); w.y = cvt_pk_bf16(v[2], v[3]); *(u32x2*)p = w; }
; __device__ __forceinline__ float dpp_ror1(float x) { float r; asm volatile("s_nop 1\n\tv_mov_b32_dpp %0, %1 row_ror:1 row_mask:0xf bank_mask:0xf" : "=v"(r) : "v"(x)); return r; }
; __device__ __forceinline__ float dpp_ror2(float x) { float r; asm volatile("s_nop 1\n\tv_mov_b32_dpp %0, %1 row_ror:2 row_mask:0xf bank_mask:0xf" : "=v"(r) : "v"(x)); return r; }
;     __device__ __forceinline__ void operator()(const f32x4 (&acc)[2][2][4][2], const Unit& u, int wr, int wc, int fr, int fq) const {
;     ...
;             const f32x4 wg0 = *(const f32x4*)(cw + col), wg1 = *(const f32x4*)(cw + 5632 + col), wg2 = *(const f32x4*)(cw + 2 * 5632 + col), bg = *(const f32x4*)(cb + col);
;             const f32x4 wv0 = *(const f32x4*)(cw + 2816 + col), wv1 = *(const f32x4*)(cw + 5632 + 2816 + col), wv2 = *(const f32x4*)(cw + 2 * 5632 + 2816 + col), bv = *(const f32x4*)(cb + 2816 + col);
;             f32x4 pg = (f32x4){0.f, 0.f, 0.f, 0.f}, pv = (f32x4){0.f, 0.f, 0.f, 0.f};
; #pragma unroll
;             for (int q = 0; q < 8; ++q) {
;                 const f32x4 ug = acc[q >> 2][0][q & 3][n] * rs[q], uv = acc[q >> 2][1][q & 3][n] * rs[q];
;                 f32x4 res;
; #pragma unroll
;                 for (int j = 0; j < 4; ++j) {
;                     const float ga1 = dpp_ror1(ug[j]), gb1 = dpp_ror1(pg[j]), ga2 = dpp_ror2(ug[j]), gb2 = dpp_ror2(pg[j]);
;                     const float va1 = dpp_ror1(uv[j]), vb1 = dpp_ror1(pv[j]), va2 = dpp_ror2(uv[j]), vb2 = dpp_ror2(pv[j]);
;                     const float g1 = fr >= 1 ? ga1 : gb1, g2 = fr >= 2 ? ga2 : gb2, v1 = fr >= 1 ? va1 : vb1, v2 = fr >= 2 ? va2 : vb2;
;                     const float cgv = bg[j] + wg0[j] * g2 + wg1[j] * g1 + wg2[j] * ug[j];
;                     const float cvv = bv[j] + wv0[j] * v2 + wv1[j] * v1 + wv2[j] * uv[j];
;                     res[j] = cgv * __builtin_amdgcn_rcpf(1.0f + __builtin_amdgcn_exp2f(-1.44269504f * cgv)) * cvv;
;                 }
;                 pg = ug; pv = uv;
;                 const int row = g0 + 16 * q;
;                 if ((q > 0 || fr >= 2) && row < SEQ) store4(ACT + (size_t)row * 2816 + col, res);
.Lupepi_skip3:
	s_or_b64 exec, exec, s[4:5]
	v_pk_mul_f32 v[126:127], v[126:127], v[176:177] op_sel_hi:[1,0]
	v_pk_mul_f32 v[128:129], v[128:129], v[176:177] op_sel_hi:[1,0]
	v_pk_mul_f32 v[122:123], v[122:123], v[176:177] op_sel_hi:[1,0]
	v_pk_mul_f32 v[124:125], v[124:125], v[176:177] op_sel_hi:[1,0]
	v_pk_mov_b32 v[180:181], v[94:95], v[94:95] op_sel:[0,1]
	v_pk_mov_b32 v[182:183], v[96:97], v[96:97] op_sel:[0,1]
	v_pk_mov_b32 v[184:185], v[110:111], v[110:111] op_sel:[0,1]
	v_pk_mov_b32 v[186:187], v[112:113], v[112:113] op_sel:[0,1]
	v_fmac_f32_dpp v180, v126, v82 row_shr:2 row_mask:0xf bank_mask:0xf
	v_fmac_f32_dpp v181, v127, v83 row_shr:2 row_mask:0xf bank_mask:0xf
	v_fmac_f32_dpp v182, v128, v84 row_shr:2 row_mask:0xf bank_mask:0xf
	v_fmac_f32_dpp v183, v129, v85 row_shr:2 row_mask:0xf bank_mask:0xf
	v_fmac_f32_dpp v184, v122, v98 row_shr:2 row_mask:0xf bank_mask:0xf
	v_fmac_f32_dpp v185, v123, v99 row_shr:2 row_mask:0xf bank_mask:0xf
	v_fmac_f32_dpp v186, v124, v100 row_shr:2 row_mask:0xf bank_mask:0xf
	v_fmac_f32_dpp v187, v125, v101 row_shr:2 row_mask:0xf bank_mask:0xf
	v_fmac_f32_dpp v180, v134, v82 row_shl:14 row_mask:0xf bank_mask:0xf
	v_fmac_f32_dpp v181, v135, v83 row_shl:14 row_mask:0xf bank_mask:0xf
	v_fmac_f32_dpp v182, v136, v84 row_shl:14 row_mask:0xf bank_mask:0xf
	v_fmac_f32_dpp v183, v137, v85 row_shl:14 row_mask:0xf bank_mask:0xf
	v_fmac_f32_dpp v184, v130, v98 row_shl:14 row_mask:0xf bank_mask:0xf
	v_fmac_f32_dpp v185, v131, v99 row_shl:14 row_mask:0xf bank_mask:0xf
	v_fmac_f32_dpp v186, v132, v100 row_shl:14 row_mask:0xf bank_mask:0xf
	v_fmac_f32_dpp v187, v133, v101 row_shl:14 row_mask:0xf bank_mask:0xf
	v_fmac_f32_dpp v180, v126, v86 row_shr:1 row_mask:0xf bank_mask:0xf
	v_fmac_f32_dpp v181, v127, v87 row_shr:1 row_mask:0xf bank_mask:0xf
	v_fmac_f32_dpp v182, v128, v88 row_shr:1 row_mask:0xf bank_mask:0xf
	v_fmac_f32_dpp v183, v129, v89 row_shr:1 row_mask:0xf bank_mask:0xf
	v_fmac_f32_dpp v184, v122, v102 row_shr:1 row_mask:0xf bank_mask:0xf
	v_fmac_f32_dpp v185, v123, v103 row_shr:1 row_mask:0xf bank_mask:0xf
	v_fmac_f32_dpp v186, v124, v104 row_shr:1 row_mask:0xf bank_mask:0xf
	v_fmac_f32_dpp v187, v125, v105 row_shr:1 row_mask:0xf bank_mask:0xf
	v_fmac_f32_dpp v180, v134, v86 row_shl:15 row_mask:0xf bank_mask:0xf
	v_fmac_f32_dpp v181, v135, v87 row_shl:15 row_mask:0xf bank_mask:0xf
	v_fmac_f32_dpp v182, v136, v88 row_shl:15 row_mask:0xf bank_mask:0xf
	v_fmac_f32_dpp v183, v137, v89 row_shl:15 row_mask:0xf bank_mask:0xf
	v_fmac_f32_dpp v184, v130, v102 row_shl:15 row_mask:0xf bank_mask:0xf
	v_fmac_f32_dpp v185, v131, v103 row_shl:15 row_mask:0xf bank_mask:0xf
	v_fmac_f32_dpp v186, v132, v104 row_shl:15 row_mask:0xf bank_mask:0xf
	v_fmac_f32_dpp v187, v133, v105 row_shl:15 row_mask:0xf bank_mask:0xf
	v_pk_fma_f32 v[180:181], v[126:127], v[90:91], v[180:181]
	v_pk_fma_f32 v[182:183], v[128:129], v[92:93], v[182:183]
	v_pk_fma_f32 v[184:185], v[122:123], v[106:107], v[184:185]
	v_pk_fma_f32 v[186:187], v[124:125], v[108:109], v[186:187]
	v_pk_mul_f32 v[188:189], v[180:181], s[12:13] op_sel_hi:[1,0]
	v_pk_mul_f32 v[190:191], v[182:183], s[12:13] op_sel_hi:[1,0]
	v_exp_f32_e32 v188, v188
	v_exp_f32_e32 v189, v189
	v_exp_f32_e32 v190, v190
	v_exp_f32_e32 v191, v191
	v_pk_add_f32 v[188:189], v[188:189], 1.0 op_sel_hi:[1,0]
	v_pk_add_f32 v[190:191], v[190:191], 1.0 op_sel_hi:[1,0]
	v_rcp_f32_e32 v188, v188
	v_rcp_f32_e32 v189, v189
	v_rcp_f32_e32 v190, v190
	v_rcp_f32_e32 v191, v191
	v_cmp_gt_i32_e32 vcc, 0x3fc0, v230
	v_pk_mul_f32 v[188:189], v[180:181], v[188:189]
	v_pk_mul_f32 v[190:191], v[182:183], v[190:191]
	v_pk_mul_f32 v[188:189], v[184:185], v[188:189]
	v_pk_mul_f32 v[190:191], v[186:187], v[190:191]
	v_add_u32_e32 v234, 0x58000, v233
	v_cvt_pk_bf16_f32 v206, v188, v189
	v_cvt_pk_bf16_f32 v207, v190, v191
	s_and_saveexec_b64 s[4:5], vcc
	s_cbranch_execz .Lupepi_skip4
	global_store_dwordx2 v234, v[206:207], s[26:27]
.Lupepi_skip4:
	s_or_b64 exec, exec, s[4:5]
	global_load_dwordx4 v[158:161], v232, s[30:31] offset:16
	global_load_dwordx4 v[154:157], v232, s[38:39] offset:16
	global_load_dwordx4 v[150:153], v232, s[40:41] offset:16
	global_load_dwordx4 v[146:149], v232, s[34:35] offset:16
	global_load_dwordx4 v[142:145], v232, s[42:43] offset:16
	global_load_dwordx4 v[138:141], v232, s[44:45] offset:16
	global_load_dwordx4 v[134:137], v232, s[46:47] offset:16
	global_load_dwordx4 v[130:133], v232, s[48:49] offset:16
	v_pk_mul_f32 v[118:119], v[118:119], v[176:177] op_sel:[0,1] op_sel_hi:[1,1]
	v_pk_mul_f32 v[120:121], v[120:121], v[176:177] op_sel:[0,1] op_sel_hi:[1,1]
	v_pk_mul_f32 v[114:115], v[114:115], v[176:177] op_sel:[0,1] op_sel_hi:[1,1]
	v_pk_mul_f32 v[116:117], v[116:117], v[176:177] op_sel:[0,1] op_sel_hi:[1,1]
	v_pk_mov_b32 v[180:181], v[94:95], v[94:95] op_sel:[0,1]
	v_pk_mov_b32 v[182:183], v[96:97], v[96:97] op_sel:[0,1]
	v_pk_mov_b32 v[184:185], v[110:111], v[110:111] op_sel:[0,1]
	v_pk_mov_b32 v[186:187], v[112:113], v[112:113] op_sel:[0,1]
	v_fmac_f32_dpp v180, v118, v82 row_shr:2 row_mask:0xf bank_mask:0xf
	v_fmac_f32_dpp v181, v119, v83 row_shr:2 row_mask:0xf bank_mask:0xf
	v_fmac_f32_dpp v182, v120, v84 row_shr:2 row_mask:0xf bank_mask:0xf
	v_fmac_f32_dpp v183, v121, v85 row_shr:2 row_mask:0xf bank_mask:0xf
	v_fmac_f32_dpp v184, v114, v98 row_shr:2 row_mask:0xf bank_mask:0xf
	v_fmac_f32_dpp v185, v115, v99 row_shr:2 row_mask:0xf bank_mask:0xf
	v_fmac_f32_dpp v186, v116, v100 row_shr:2 row_mask:0xf bank_mask:0xf
	v_fmac_f32_dpp v187, v117, v101 row_shr:2 row_mask:0xf bank_mask:0xf
	v_fmac_f32_dpp v180, v126, v82 row_shl:14 row_mask:0xf bank_mask:0xf
; __device__ __forceinline__ void store4(bf16_t* p, f32x4 v) { u32x2 w; w.x = cvt_pk_bf16(v[0], v[1]); w.y = cvt_pk_bf16(v[2], v[3]); *(u32x2*)p = w; }
; __device__ __forceinline__ float dpp_ror1(float x) { float r; asm volatile("s_nop 1\n\tv_mov_b32_dpp %0, %1 row_ror:1 row_mask:0xf bank_mask:0xf" : "=v"(r) : "v"(x)); return r; }
; __device__ __forceinline__ float dpp_ror2(float x) { float r; asm volatile("s_nop 1\n\tv_mov_b32_dpp %0, %1 row_ror:2 row_mask:0xf bank_mask:0xf" : "=v"(r) : "v"(x)); return r; }
;     __device__ __forceinline__ void operator()(const f32x4 (&acc)[2][2][4][2], const Unit& u, int wr, int wc, int fr, int fq) const {
;     ...
; #pragma unroll
;             for (int q = 0; q < 8; ++q) {
;                 const f32x4 ug = acc[q >> 2][0][q & 3][n] * rs[q], uv = acc[q >> 2][1][q & 3][n] * rs[q];
;                 f32x4 res;
; #pragma unroll
;                 for (int j = 0; j < 4; ++j) {
;                     const float ga1 = dpp_ror1(ug[j]), gb1 = dpp_ror1(pg[j]), ga2 = dpp_ror2(ug[j]), gb2 = dpp_ror2(pg[j]);
;                     const float va1 = dpp_ror1(uv[j]), vb1 = dpp_ror1(pv[j]), va2 = dpp_ror2(uv[j]), vb2 = dpp_ror2(pv[j]);
;                     const float g1 = fr >= 1 ? ga1 : gb1, g2 = fr >= 2 ? ga2 : gb2, v1 = fr >= 1 ? va1 : vb1, v2 = fr >= 2 ? va2 : vb2;
;                     const float cgv = bg[j] + wg0[j] * g2 + wg1[j] * g1 + wg2[j] * ug[j];
;                     const float cvv = bv[j] + wv0[j] * v2 + wv1[j] * v1 + wv2[j] * uv[j];
;                     res[j] = cgv * __builtin_amdgcn_rcpf(1.0f + __builtin_amdgcn_exp2f(-1.44269504f * cgv)) * cvv;
;                 }
;                 pg = ug; pv = uv;
;                 const int row = g0 + 16 * q;
;                 if ((q > 0 || fr >= 2) && row < SEQ) store4(ACT + (size_t)row * 2816 + col, res);
	v_fmac_f32_dpp v181, v127, v83 row_shl:14 row_mask:0xf bank_mask:0xf
	v_fmac_f32_dpp v182, v128, v84 row_shl:14 row_mask:0xf bank_mask:0xf
	v_fmac_f32_dpp v183, v129, v85 row_shl:14 row_mask:0xf bank_mask:0xf
	v_fmac_f32_dpp v184, v122, v98 row_shl:14 row_mask:0xf bank_mask:0xf
	v_fmac_f32_dpp v185, v123, v99 row_shl:14 row_mask:0xf bank_mask:0xf
	v_fmac_f32_dpp v186, v124, v100 row_shl:14 row_mask:0xf bank_mask:0xf
	v_fmac_f32_dpp v187, v125, v101 row_shl:14 row_mask:0xf bank_mask:0xf
	v_fmac_f32_dpp v180, v118, v86 row_shr:1 row_mask:0xf bank_mask:0xf
	v_fmac_f32_dpp v181, v119, v87 row_shr:1 row_mask:0xf bank_mask:0xf
	v_fmac_f32_dpp v182, v120, v88 row_shr:1 row_mask:0xf bank_mask:0xf
	v_fmac_f32_dpp v183, v121, v89 row_shr:1 row_mask:0xf bank_mask:0xf
	v_fmac_f32_dpp v184, v114, v102 row_shr:1 row_mask:0xf bank_mask:0xf
	v_fmac_f32_dpp v185, v115, v103 row_shr:1 row_mask:0xf bank_mask:0xf
	v_fmac_f32_dpp v186, v116, v104 row_shr:1 row_mask:0xf bank_mask:0xf
	v_fmac_f32_dpp v187, v117, v105 row_shr:1 row_mask:0xf bank_mask:0xf
	v_fmac_f32_dpp v180, v126, v86 row_shl:15 row_mask:0xf bank_mask:0xf
	v_fmac_f32_dpp v181, v127, v87 row_shl:15 row_mask:0xf bank_mask:0xf
	v_fmac_f32_dpp v182, v128, v88 row_shl:15 row_mask:0xf bank_mask:0xf
	v_fmac_f32_dpp v183, v129, v89 row_shl:15 row_mask:0xf bank_mask:0xf
	v_fmac_f32_dpp v184, v122, v102 row_shl:15 row_mask:0xf bank_mask:0xf
	v_fmac_f32_dpp v185, v123, v103 row_shl:15 row_mask:0xf bank_mask:0xf
	v_fmac_f32_dpp v186, v124, v104 row_shl:15 row_mask:0xf bank_mask:0xf
	v_fmac_f32_dpp v187, v125, v105 row_shl:15 row_mask:0xf bank_mask:0xf
	v_pk_fma_f32 v[180:181], v[118:119], v[90:91], v[180:181]
	v_pk_fma_f32 v[182:183], v[120:121], v[92:93], v[182:183]
	v_pk_fma_f32 v[184:185], v[114:115], v[106:107], v[184:185]
	v_pk_fma_f32 v[186:187], v[116:117], v[108:109], v[186:187]
	v_pk_mul_f32 v[188:189], v[180:181], s[12:13] op_sel_hi:[1,0]
	v_pk_mul_f32 v[190:191], v[182:183], s[12:13] op_sel_hi:[1,0]
	v_exp_f32_e32 v188, v188
	v_exp_f32_e32 v189, v189
	v_exp_f32_e32 v190, v190
	v_exp_f32_e32 v191, v191
	v_pk_add_f32 v[188:189], v[188:189], 1.0 op_sel_hi:[1,0]
	v_pk_add_f32 v[190:191], v[190:191], 1.0 op_sel_hi:[1,0]
	v_rcp_f32_e32 v188, v188
	v_rcp_f32_e32 v189, v189
	v_rcp_f32_e32 v190, v190
	v_rcp_f32_e32 v191, v191
	v_cmp_gt_i32_e32 vcc, 0x3fb0, v230
	v_pk_mul_f32 v[188:189], v[180:181], v[188:189]
	v_pk_mul_f32 v[190:191], v[182:183], v[190:191]
	v_pk_mul_f32 v[188:189], v[184:185], v[188:189]
	v_pk_mul_f32 v[190:191], v[186:187], v[190:191]
	v_add_u32_e32 v234, 0x6e000, v233
	v_cvt_pk_bf16_f32 v208, v188, v189
	v_cvt_pk_bf16_f32 v209, v190, v191
	s_and_saveexec_b64 s[4:5], vcc
	s_cbranch_execz .Lupepi_skip5
	global_store_dwordx2 v234, v[208:209], s[26:27]
.Lupepi_skip5:
	s_or_b64 exec, exec, s[4:5]
	v_pk_mul_f32 v[78:79], v[78:79], v[178:179] op_sel_hi:[1,0]
	v_pk_mul_f32 v[80:81], v[80:81], v[178:179] op_sel_hi:[1,0]
	v_pk_mul_f32 v[74:75], v[74:75], v[178:179] op_sel_hi:[1,0]
	v_pk_mul_f32 v[76:77], v[76:77], v[178:179] op_sel_hi:[1,0]
	v_pk_mov_b32 v[180:181], v[94:95], v[94:95] op_sel:[0,1]
	v_pk_mov_b32 v[182:183], v[96:97], v[96:97] op_sel:[0,1]
	v_pk_mov_b32 v[184:185], v[110:111], v[110:111] op_sel:[0,1]
	v_pk_mov_b32 v[186:187], v[112:113], v[112:113] op_sel:[0,1]
	v_fmac_f32_dpp v180, v78, v82 row_shr:2 row_mask:0xf bank_mask:0xf
	v_fmac_f32_dpp v181, v79, v83 row_shr:2 row_mask:0xf bank_mask:0xf
	v_fmac_f32_dpp v182, v80, v84 row_shr:2 row_mask:0xf bank_mask:0xf
	v_fmac_f32_dpp v183, v81, v85 row_shr:2 row_mask:0xf bank_mask:0xf
	v_fmac_f32_dpp v184, v74, v98 row_shr:2 row_mask:0xf bank_mask:0xf
	v_fmac_f32_dpp v185, v75, v99 row_shr:2 row_mask:0xf bank_mask:0xf
	v_fmac_f32_dpp v186, v76, v100 row_shr:2 row_mask:0xf bank_mask:0xf
	v_fmac_f32_dpp v187, v77, v101 row_shr:2 row_mask:0xf bank_mask:0xf
	v_fmac_f32_dpp v180, v118, v82 row_shl:14 row_mask:0xf bank_mask:0xf
	v_fmac_f32_dpp v181, v119, v83 row_shl:14 row_mask:0xf bank_mask:0xf
	v_fmac_f32_dpp v182, v120, v84 row_shl:14 row_mask:0xf bank_mask:0xf
	v_fmac_f32_dpp v183, v121, v85 row_shl:14 row_mask:0xf bank_mask:0xf
	v_fmac_f32_dpp v184, v114, v98 row_shl:14 row_mask:0xf bank_mask:0xf
	v_fmac_f32_dpp v185, v115, v99 row_shl:14 row_mask:0xf bank_mask:0xf
	v_fmac_f32_dpp v186, v116, v100 row_shl:14 row_mask:0xf bank_mask:0xf
	v_fmac_f32_dpp v187, v117, v101 row_shl:14 row_mask:0xf bank_mask:0xf
	v_fmac_f32_dpp v180, v78, v86 row_shr:1 row_mask:0xf bank_mask:0xf
	v_fmac_f32_dpp v181, v79, v87 row_shr:1 row_mask:0xf bank_mask:0xf
	v_fmac_f32_dpp v182, v80, v88 row_shr:1 row_mask:0xf bank_mask:0xf
	v_fmac_f32_dpp v183, v81, v89 row_shr:1 row_mask:0xf bank_mask:0xf
	v_fmac_f32_dpp v184, v74, v102 row_shr:1 row_mask:0xf bank_mask:0xf
	v_fmac_f32_dpp v185, v75, v103 row_shr:1 row_mask:0xf bank_mask:0xf
	v_fmac_f32_dpp v186, v76, v104 row_shr:1 row_mask:0xf bank_mask:0xf
	v_fmac_f32_dpp v187, v77, v105 row_shr:1 row_mask:0xf bank_mask:0xf
	v_fmac_f32_dpp v180, v118, v86 row_shl:15 row_mask:0xf bank_mask:0xf
	v_fmac_f32_dpp v181, v119, v87 row_shl:15 row_mask:0xf bank_mask:0xf
	v_fmac_f32_dpp v182, v120, v88 row_shl:15 row_mask:0xf bank_mask:0xf
	v_fmac_f32_dpp v183, v121, v89 row_shl:15 row_mask:0xf bank_mask:0xf
	v_fmac_f32_dpp v184, v114, v102 row_shl:15 row_mask:0xf bank_mask:0xf
	v_fmac_f32_dpp v185, v115, v103 row_shl:15 row_mask:0xf bank_mask:0xf
	v_fmac_f32_dpp v186, v116, v104 row_shl:15 row_mask:0xf bank_mask:0xf
	v_fmac_f32_dpp v187, v117, v105 row_shl:15 row_mask:0xf bank_mask:0xf
	v_pk_fma_f32 v[180:181], v[78:79], v[90:91], v[180:181]
	v_pk_fma_f32 v[182:183], v[80:81], v[92:93], v[182:183]
	v_pk_fma_f32 v[184:185], v[74:75], v[106:107], v[184:185]
	v_pk_fma_f32 v[186:187], v[76:77], v[108:109], v[186:187]
	v_pk_mul_f32 v[188:189], v[180:181], s[12:13] op_sel_hi:[1,0]
	v_pk_mul_f32 v[190:191], v[182:183], s[12:13] op_sel_hi:[1,0]
	v_exp_f32_e32 v188, v188
	v_exp_f32_e32 v189, v189
	v_exp_f32_e32 v190, v190
	v_exp_f32_e32 v191, v191
	v_pk_add_f32 v[188:189], v[188:189], 1.0 op_sel_hi:[1,0]
	v_pk_add_f32 v[190:191], v[190:191], 1.0 op_sel_hi:[1,0]
	v_rcp_f32_e32 v188, v188
	v_rcp_f32_e32 v189, v189
	v_rcp_f32_e32 v190, v190
	v_rcp_f32_e32 v191, v191
	v_cmp_gt_i32_e32 vcc, 0x3fa0, v230
	v_pk_mul_f32 v[188:189], v[180:181], v[188:189]
	v_pk_mul_f32 v[190:191], v[182:183], v[190:191]
	v_pk_mul_f32 v[188:189], v[184:185], v[188:189]
	v_pk_mul_f32 v[190:191], v[186:187], v[190:191]
	v_add_u32_e32 v234, 0x84000, v233
	v_cvt_pk_bf16_f32 v206, v188, v189
	v_cvt_pk_bf16_f32 v207, v190, v191
	s_and_saveexec_b64 s[4:5], vcc
	s_cbranch_execz .Lupepi_skip6
	global_store_dwordx2 v234, v[206:207], s[26:27]
; __device__ __forceinline__ void store4(bf16_t* p, f32x4 v) { u32x2 w; w.x = cvt_pk_bf16(v[0], v[1]); w.y = cvt_pk_bf16(v[2], v[3]); *(u32x2*)p = w; }
; __device__ __forceinline__ float dpp_ror1(float x) { float r; asm volatile("s_nop 1\n\tv_mov_b32_dpp %0, %1 row_ror:1 row_mask:0xf bank_mask:0xf" : "=v"(r) : "v"(x)); return r; }
; __device__ __forceinline__ float dpp_ror2(float x) { float r; asm volatile("s_nop 1\n\tv_mov_b32_dpp %0, %1 row_ror:2 row_mask:0xf bank_mask:0xf" : "=v"(r) : "v"(x)); return r; }
;     __device__ __forceinline__ void operator()(const f32x4 (&acc)[2][2][4][2], const Unit& u, int wr, int wc, int fr, int fq) const {
;     ...
; #pragma unroll
;         for (int n = 0; n < 2; ++n) {
;             const int col = 128 * u.pn + 32 * wc + 8 * fq + 4 * n;
;             const f32x4 wg0 = *(const f32x4*)(cw + col), wg1 = *(const f32x4*)(cw + 5632 + col), wg2 = *(const f32x4*)(cw + 2 * 5632 + col), bg = *(const f32x4*)(cb + col);
;             const f32x4 wv0 = *(const f32x4*)(cw + 2816 + col), wv1 = *(const f32x4*)(cw + 5632 + 2816 + col), wv2 = *(const f32x4*)(cw + 2 * 5632 + 2816 + col), bv = *(const f32x4*)(cb + 2816 + col);
;             f32x4 pg = (f32x4){0.f, 0.f, 0.f, 0.f}, pv = (f32x4){0.f, 0.f, 0.f, 0.f};
; #pragma unroll
;             for (int q = 0; q < 8; ++q) {
;                 const f32x4 ug = acc[q >> 2][0][q & 3][n] * rs[q], uv = acc[q >> 2][1][q & 3][n] * rs[q];
;                 f32x4 res;
; #pragma unroll
;                 for (int j = 0; j < 4; ++j) {
;                     const float ga1 = dpp_ror1(ug[j]), gb1 = dpp_ror1(pg[j]), ga2 = dpp_ror2(ug[j]), gb2 = dpp_ror2(pg[j]);
;                     const float va1 = dpp_ror1(uv[j]), vb1 = dpp_ror1(pv[j]), va2 = dpp_ror2(uv[j]), vb2 = dpp_ror2(pv[j]);
;                     const float g1 = fr >= 1 ? ga1 : gb1, g2 = fr >= 2 ? ga2 : gb2, v1 = fr >= 1 ? va1 : vb1, v2 = fr >= 2 ? va2 : vb2;
;                     const float cgv = bg[j] + wg0[j] * g2 + wg1[j] * g1 + wg2[j] * ug[j];
;                     const float cvv = bv[j] + wv0[j] * v2 + wv1[j] * v1 + wv2[j] * uv[j];
;                     res[j] = cgv * __builtin_amdgcn_rcpf(1.0f + __builtin_amdgcn_exp2f(-1.44269504f * cgv)) * cvv;
;                 }
;                 pg = ug; pv = uv;
;                 const int row = g0 + 16 * q;
;                 if ((q > 0 || fr >= 2) && row < SEQ) store4(ACT + (size_t)row * 2816 + col, res);
.Lupepi_skip6:
	s_or_b64 exec, exec, s[4:5]
	v_pk_mul_f32 v[70:71], v[70:71], v[178:179] op_sel:[0,1] op_sel_hi:[1,1]
	v_pk_mul_f32 v[72:73], v[72:73], v[178:179] op_sel:[0,1] op_sel_hi:[1,1]
	v_pk_mul_f32 v[66:67], v[66:67], v[178:179] op_sel:[0,1] op_sel_hi:[1,1]
	v_pk_mul_f32 v[68:69], v[68:69], v[178:179] op_sel:[0,1] op_sel_hi:[1,1]
	v_pk_mov_b32 v[180:181], v[94:95], v[94:95] op_sel:[0,1]
	v_pk_mov_b32 v[182:183], v[96:97], v[96:97] op_sel:[0,1]
	v_pk_mov_b32 v[184:185], v[110:111], v[110:111] op_sel:[0,1]
	v_pk_mov_b32 v[186:187], v[112:113], v[112:113] op_sel:[0,1]
	v_fmac_f32_dpp v180, v70, v82 row_shr:2 row_mask:0xf bank_mask:0xf
	v_fmac_f32_dpp v181, v71, v83 row_shr:2 row_mask:0xf bank_mask:0xf
	v_fmac_f32_dpp v182, v72, v84 row_shr:2 row_mask:0xf bank_mask:0xf
	v_fmac_f32_dpp v183, v73, v85 row_shr:2 row_mask:0xf bank_mask:0xf
	v_fmac_f32_dpp v184, v66, v98 row_shr:2 row_mask:0xf bank_mask:0xf
	v_fmac_f32_dpp v185, v67, v99 row_shr:2 row_mask:0xf bank_mask:0xf
	v_fmac_f32_dpp v186, v68, v100 row_shr:2 row_mask:0xf bank_mask:0xf
	v_fmac_f32_dpp v187, v69, v101 row_shr:2 row_mask:0xf bank_mask:0xf
	v_fmac_f32_dpp v180, v78, v82 row_shl:14 row_mask:0xf bank_mask:0xf
	v_fmac_f32_dpp v181, v79, v83 row_shl:14 row_mask:0xf bank_mask:0xf
	v_fmac_f32_dpp v182, v80, v84 row_shl:14 row_mask:0xf bank_mask:0xf
	v_fmac_f32_dpp v183, v81, v85 row_shl:14 row_mask:0xf bank_mask:0xf
	v_fmac_f32_dpp v184, v74, v98 row_shl:14 row_mask:0xf bank_mask:0xf
	v_fmac_f32_dpp v185, v75, v99 row_shl:14 row_mask:0xf bank_mask:0xf
	v_fmac_f32_dpp v186, v76, v100 row_shl:14 row_mask:0xf bank_mask:0xf
	v_fmac_f32_dpp v187, v77, v101 row_shl:14 row_mask:0xf bank_mask:0xf
	v_fmac_f32_dpp v180, v70, v86 row_shr:1 row_mask:0xf bank_mask:0xf
	v_fmac_f32_dpp v181, v71, v87 row_shr:1 row_mask:0xf bank_mask:0xf
	v_fmac_f32_dpp v182, v72, v88 row_shr:1 row_mask:0xf bank_mask:0xf
	v_fmac_f32_dpp v183, v73, v89 row_shr:1 row_mask:0xf bank_mask:0xf
	v_fmac_f32_dpp v184, v66, v102 row_shr:1 row_mask:0xf bank_mask:0xf
	v_fmac_f32_dpp v185, v67, v103 row_shr:1 row_mask:0xf bank_mask:0xf
	v_fmac_f32_dpp v186, v68, v104 row_shr:1 row_mask:0xf bank_mask:0xf
	v_fmac_f32_dpp v187, v69, v105 row_shr:1 row_mask:0xf bank_mask:0xf
	v_fmac_f32_dpp v180, v78, v86 row_shl:15 row_mask:0xf bank_mask:0xf
	v_fmac_f32_dpp v181, v79, v87 row_shl:15 row_mask:0xf bank_mask:0xf
	v_fmac_f32_dpp v182, v80, v88 row_shl:15 row_mask:0xf bank_mask:0xf
	v_fmac_f32_dpp v183, v81, v89 row_shl:15 row_mask:0xf bank_mask:0xf
	v_fmac_f32_dpp v184, v74, v102 row_shl:15 row_mask:0xf bank_mask:0xf
	v_fmac_f32_dpp v185, v75, v103 row_shl:15 row_mask:0xf bank_mask:0xf
	v_fmac_f32_dpp v186, v76, v104 row_shl:15 row_mask:0xf bank_mask:0xf
	v_fmac_f32_dpp v187, v77, v105 row_shl:15 row_mask:0xf bank_mask:0xf
	v_pk_fma_f32 v[180:181], v[70:71], v[90:91], v[180:181]
	v_pk_fma_f32 v[182:183], v[72:73], v[92:93], v[182:183]
	v_pk_fma_f32 v[184:185], v[66:67], v[106:107], v[184:185]
	v_pk_fma_f32 v[186:187], v[68:69], v[108:109], v[186:187]
	v_pk_mul_f32 v[188:189], v[180:181], s[12:13] op_sel_hi:[1,0]
	v_pk_mul_f32 v[190:191], v[182:183], s[12:13] op_sel_hi:[1,0]
	v_exp_f32_e32 v188, v188
	v_exp_f32_e32 v189, v189
	v_exp_f32_e32 v190, v190
	v_exp_f32_e32 v191, v191
	v_pk_add_f32 v[188:189], v[188:189], 1.0 op_sel_hi:[1,0]
	v_pk_add_f32 v[190:191], v[190:191], 1.0 op_sel_hi:[1,0]
	v_rcp_f32_e32 v188, v188
	v_rcp_f32_e32 v189, v189
	v_rcp_f32_e32 v190, v190
	v_rcp_f32_e32 v191, v191
	v_cmp_gt_i32_e32 vcc, 0x3f90, v230
	v_pk_mul_f32 v[188:189], v[180:181], v[188:189]
	v_pk_mul_f32 v[190:191], v[182:183], v[190:191]
	v_pk_mul_f32 v[188:189], v[184:185], v[188:189]
	v_pk_mul_f32 v[190:191], v[186:187], v[190:191]
	v_add_u32_e32 v234, 0x9a000, v233
	v_cvt_pk_bf16_f32 v208, v188, v189
	v_cvt_pk_bf16_f32 v209, v190, v191
	s_and_saveexec_b64 s[4:5], vcc
	s_cbranch_execz .Lupepi_skip7
	global_store_dwordx2 v234, v[208:209], s[26:27]
.Lupepi_skip7:
	s_or_b64 exec, exec, s[4:5]
	s_waitcnt vmcnt(0)
	v_pk_mul_f32 v[62:63], v[62:63], v[172:173] op_sel_hi:[1,0]
	v_pk_mul_f32 v[64:65], v[64:65], v[172:173] op_sel_hi:[1,0]
	v_pk_mul_f32 v[58:59], v[58:59], v[172:173] op_sel_hi:[1,0]
	v_pk_mul_f32 v[60:61], v[60:61], v[172:173] op_sel_hi:[1,0]
	v_pk_mov_b32 v[180:181], v[146:147], v[146:147] op_sel:[0,1]
	v_pk_mov_b32 v[182:183], v[148:149], v[148:149] op_sel:[0,1]
	v_pk_mov_b32 v[184:185], v[130:131], v[130:131] op_sel:[0,1]
	v_pk_mov_b32 v[186:187], v[132:133], v[132:133] op_sel:[0,1]
	v_fmac_f32_dpp v180, v62, v158 row_shr:2 row_mask:0xf bank_mask:0xf
	v_fmac_f32_dpp v181, v63, v159 row_shr:2 row_mask:0xf bank_mask:0xf
	v_fmac_f32_dpp v182, v64, v160 row_shr:2 row_mask:0xf bank_mask:0xf
	v_fmac_f32_dpp v183, v65, v161 row_shr:2 row_mask:0xf bank_mask:0xf
	v_fmac_f32_dpp v184, v58, v142 row_shr:2 row_mask:0xf bank_mask:0xf
	v_fmac_f32_dpp v185, v59, v143 row_shr:2 row_mask:0xf bank_mask:0xf
	v_fmac_f32_dpp v186, v60, v144 row_shr:2 row_mask:0xf bank_mask:0xf
	v_fmac_f32_dpp v187, v61, v145 row_shr:2 row_mask:0xf bank_mask:0xf
	v_fmac_f32_dpp v180, v62, v154 row_shr:1 row_mask:0xf bank_mask:0xf
	v_fmac_f32_dpp v181, v63, v155 row_shr:1 row_mask:0xf bank_mask:0xf
	v_fmac_f32_dpp v182, v64, v156 row_shr:1 row_mask:0xf bank_mask:0xf
	v_fmac_f32_dpp v183, v65, v157 row_shr:1 row_mask:0xf bank_mask:0xf
	v_fmac_f32_dpp v184, v58, v138 row_shr:1 row_mask:0xf bank_mask:0xf
	v_fmac_f32_dpp v185, v59, v139 row_shr:1 row_mask:0xf bank_mask:0xf
	v_fmac_f32_dpp v186, v60, v140 row_shr:1 row_mask:0xf bank_mask:0xf
	v_fmac_f32_dpp v187, v61, v141 row_shr:1 row_mask:0xf bank_mask:0xf
	v_pk_fma_f32 v[180:181], v[62:63], v[150:151], v[180:181]
	v_pk_fma_f32 v[182:183], v[64:65], v[152:153], v[182:183]
	v_pk_fma_f32 v[184:185], v[58:59], v[134:135], v[184:185]
	v_pk_fma_f32 v[186:187], v[60:61], v[136:137], v[186:187]
	v_pk_mul_f32 v[188:189], v[180:181], s[12:13] op_sel_hi:[1,0]
	v_pk_mul_f32 v[190:191], v[182:183], s[12:13] op_sel_hi:[1,0]
	v_exp_f32_e32 v188, v188
	v_exp_f32_e32 v189, v189
	v_exp_f32_e32 v190, v190
	v_exp_f32_e32 v191, v191
	v_pk_add_f32 v[188:189], v[188:189], 1.0 op_sel_hi:[1,0]
	v_pk_add_f32 v[190:191], v[190:191], 1.0 op_sel_hi:[1,0]
	v_rcp_f32_e32 v188, v188
	v_rcp_f32_e32 v189, v189
	v_rcp_f32_e32 v190, v190
	v_rcp_f32_e32 v191, v191
	v_cmp_gt_i32_e32 vcc, 0x4000, v230
	v_pk_mul_f32 v[188:189], v[180:181], v[188:189]
	v_pk_mul_f32 v[190:191], v[182:183], v[190:191]
	v_pk_mul_f32 v[188:189], v[184:185], v[188:189]
	v_pk_mul_f32 v[190:191], v[186:187], v[190:191]
	s_and_b64 vcc, vcc, s[8:9]
	v_cvt_pk_bf16_f32 v206, v188, v189
	v_cvt_pk_bf16_f32 v207, v190, v191
	s_and_saveexec_b64 s[4:5], vcc
	s_cbranch_execz .Lupepi_skip8
	global_store_dwordx2 v233, v[206:207], s[26:27] offset:8
; __device__ __forceinline__ void store4(bf16_t* p, f32x4 v) { u32x2 w; w.x = cvt_pk_bf16(v[0], v[1]); w.y = cvt_pk_bf16(v[2], v[3]); *(u32x2*)p = w; }
; __device__ __forceinline__ float dpp_ror1(float x) { float r; asm volatile("s_nop 1\n\tv_mov_b32_dpp %0, %1 row_ror:1 row_mask:0xf bank_mask:0xf" : "=v"(r) : "v"(x)); return r; }
; __device__ __forceinline__ float dpp_ror2(float x) { float r; asm volatile("s_nop 1\n\tv_mov_b32_dpp %0, %1 row_ror:2 row_mask:0xf bank_mask:0xf" : "=v"(r) : "v"(x)); return r; }
;     __device__ __forceinline__ void operator()(const f32x4 (&acc)[2][2][4][2], const Unit& u, int wr, int wc, int fr, int fq) const {
;     ...
; #pragma unroll
;             for (int q = 0; q < 8; ++q) {
;                 const f32x4 ug = acc[q >> 2][0][q & 3][n] * rs[q], uv = acc[q >> 2][1][q & 3][n] * rs[q];
;                 f32x4 res;
; #pragma unroll
;                 for (int j = 0; j < 4; ++j) {
;                     const float ga1 = dpp_ror1(ug[j]), gb1 = dpp_ror1(pg[j]), ga2 = dpp_ror2(ug[j]), gb2 = dpp_ror2(pg[j]);
;                     const float va1 = dpp_ror1(uv[j]), vb1 = dpp_ror1(pv[j]), va2 = dpp_ror2(uv[j]), vb2 = dpp_ror2(pv[j]);
;                     const float g1 = fr >= 1 ? ga1 : gb1, g2 = fr >= 2 ? ga2 : gb2, v1 = fr >= 1 ? va1 : vb1, v2 = fr >= 2 ? va2 : vb2;
;                     const float cgv = bg[j] + wg0[j] * g2 + wg1[j] * g1 + wg2[j] * ug[j];
;                     const float cvv = bv[j] + wv0[j] * v2 + wv1[j] * v1 + wv2[j] * uv[j];
;                     res[j] = cgv * __builtin_amdgcn_rcpf(1.0f + __builtin_amdgcn_exp2f(-1.44269504f * cgv)) * cvv;
;                 }
;                 pg = ug; pv = uv;
;                 const int row = g0 + 16 * q;
;                 if ((q > 0 || fr >= 2) && row < SEQ) store4(ACT + (size_t)row * 2816 + col, res);
.Lupepi_skip8:
	s_or_b64 exec, exec, s[4:5]
	v_pk_mul_f32 v[54:55], v[54:55], v[172:173] op_sel:[0,1] op_sel_hi:[1,1]
	v_pk_mul_f32 v[56:57], v[56:57], v[172:173] op_sel:[0,1] op_sel_hi:[1,1]
	v_pk_mul_f32 v[50:51], v[50:51], v[172:173] op_sel:[0,1] op_sel_hi:[1,1]
	v_pk_mul_f32 v[52:53], v[52:53], v[172:173] op_sel:[0,1] op_sel_hi:[1,1]
	v_pk_mov_b32 v[180:181], v[146:147], v[146:147] op_sel:[0,1]
	v_pk_mov_b32 v[182:183], v[148:149], v[148:149] op_sel:[0,1]
	v_pk_mov_b32 v[184:185], v[130:131], v[130:131] op_sel:[0,1]
	v_pk_mov_b32 v[186:187], v[132:133], v[132:133] op_sel:[0,1]
	v_fmac_f32_dpp v180, v54, v158 row_shr:2 row_mask:0xf bank_mask:0xf
	v_fmac_f32_dpp v181, v55, v159 row_shr:2 row_mask:0xf bank_mask:0xf
	v_fmac_f32_dpp v182, v56, v160 row_shr:2 row_mask:0xf bank_mask:0xf
	v_fmac_f32_dpp v183, v57, v161 row_shr:2 row_mask:0xf bank_mask:0xf
	v_fmac_f32_dpp v184, v50, v142 row_shr:2 row_mask:0xf bank_mask:0xf
	v_fmac_f32_dpp v185, v51, v143 row_shr:2 row_mask:0xf bank_mask:0xf
	v_fmac_f32_dpp v186, v52, v144 row_shr:2 row_mask:0xf bank_mask:0xf
	v_fmac_f32_dpp v187, v53, v145 row_shr:2 row_mask:0xf bank_mask:0xf
	v_fmac_f32_dpp v180, v62, v158 row_shl:14 row_mask:0xf bank_mask:0xf
	v_fmac_f32_dpp v181, v63, v159 row_shl:14 row_mask:0xf bank_mask:0xf
	v_fmac_f32_dpp v182, v64, v160 row_shl:14 row_mask:0xf bank_mask:0xf
	v_fmac_f32_dpp v183, v65, v161 row_shl:14 row_mask:0xf bank_mask:0xf
	v_fmac_f32_dpp v184, v58, v142 row_shl:14 row_mask:0xf bank_mask:0xf
	v_fmac_f32_dpp v185, v59, v143 row_shl:14 row_mask:0xf bank_mask:0xf
	v_fmac_f32_dpp v186, v60, v144 row_shl:14 row_mask:0xf bank_mask:0xf
	v_fmac_f32_dpp v187, v61, v145 row_shl:14 row_mask:0xf bank_mask:0xf
	v_fmac_f32_dpp v180, v54, v154 row_shr:1 row_mask:0xf bank_mask:0xf
	v_fmac_f32_dpp v181, v55, v155 row_shr:1 row_mask:0xf bank_mask:0xf
	v_fmac_f32_dpp v182, v56, v156 row_shr:1 row_mask:0xf bank_mask:0xf
	v_fmac_f32_dpp v183, v57, v157 row_shr:1 row_mask:0xf bank_mask:0xf
	v_fmac_f32_dpp v184, v50, v138 row_shr:1 row_mask:0xf bank_mask:0xf
	v_fmac_f32_dpp v185, v51, v139 row_shr:1 row_mask:0xf bank_mask:0xf
	v_fmac_f32_dpp v186, v52, v140 row_shr:1 row_mask:0xf bank_mask:0xf
	v_fmac_f32_dpp v187, v53, v141 row_shr:1 row_mask:0xf bank_mask:0xf
	v_fmac_f32_dpp v180, v62, v154 row_shl:15 row_mask:0xf bank_mask:0xf
	v_fmac_f32_dpp v181, v63, v155 row_shl:15 row_mask:0xf bank_mask:0xf
	v_fmac_f32_dpp v182, v64, v156 row_shl:15 row_mask:0xf bank_mask:0xf
	v_fmac_f32_dpp v183, v65, v157 row_shl:15 row_mask:0xf bank_mask:0xf
	v_fmac_f32_dpp v184, v58, v138 row_shl:15 row_mask:0xf bank_mask:0xf
	v_fmac_f32_dpp v185, v59, v139 row_shl:15 row_mask:0xf bank_mask:0xf
	v_fmac_f32_dpp v186, v60, v140 row_shl:15 row_mask:0xf bank_mask:0xf
	v_fmac_f32_dpp v187, v61, v141 row_shl:15 row_mask:0xf bank_mask:0xf
	v_pk_fma_f32 v[180:181], v[54:55], v[150:151], v[180:181]
	v_pk_fma_f32 v[182:183], v[56:57], v[152:153], v[182:183]
	v_pk_fma_f32 v[184:185], v[50:51], v[134:135], v[184:185]
	v_pk_fma_f32 v[186:187], v[52:53], v[136:137], v[186:187]
	v_pk_mul_f32 v[188:189], v[180:181], s[12:13] op_sel_hi:[1,0]
	v_pk_mul_f32 v[190:191], v[182:183], s[12:13] op_sel_hi:[1,0]
	v_exp_f32_e32 v188, v188
	v_exp_f32_e32 v189, v189
	v_exp_f32_e32 v190, v190
	v_exp_f32_e32 v191, v191
	v_pk_add_f32 v[188:189], v[188:189], 1.0 op_sel_hi:[1,0]
	v_pk_add_f32 v[190:191], v[190:191], 1.0 op_sel_hi:[1,0]
	v_rcp_f32_e32 v188, v188
	v_rcp_f32_e32 v189, v189
	v_rcp_f32_e32 v190, v190
	v_rcp_f32_e32 v191, v191
	v_cmp_gt_i32_e32 vcc, 0x3ff0, v230
	v_pk_mul_f32 v[188:189], v[180:181], v[188:189]
	v_pk_mul_f32 v[190:191], v[182:183], v[190:191]
	v_pk_mul_f32 v[188:189], v[184:185], v[188:189]
	v_pk_mul_f32 v[190:191], v[186:187], v[190:191]
	v_add_u32_e32 v234, 0x16000, v233
	v_cvt_pk_bf16_f32 v208, v188, v189
	v_cvt_pk_bf16_f32 v209, v190, v191
	s_and_saveexec_b64 s[4:5], vcc
	s_cbranch_execz .Lupepi_skip9
	global_store_dwordx2 v234, v[208:209], s[26:27] offset:8
.Lupepi_skip9:
	s_or_b64 exec, exec, s[4:5]
	v_pk_mul_f32 v[46:47], v[46:47], v[174:175] op_sel_hi:[1,0]
	v_pk_mul_f32 v[48:49], v[48:49], v[174:175] op_sel_hi:[1,0]
	v_pk_mul_f32 v[42:43], v[42:43], v[174:175] op_sel_hi:[1,0]
	v_pk_mul_f32 v[44:45], v[44:45], v[174:175] op_sel_hi:[1,0]
	v_pk_mov_b32 v[180:181], v[146:147], v[146:147] op_sel:[0,1]
	v_pk_mov_b32 v[182:183], v[148:149], v[148:149] op_sel:[0,1]
	v_pk_mov_b32 v[184:185], v[130:131], v[130:131] op_sel:[0,1]
	v_pk_mov_b32 v[186:187], v[132:133], v[132:133] op_sel:[0,1]
	v_fmac_f32_dpp v180, v46, v158 row_shr:2 row_mask:0xf bank_mask:0xf
	v_fmac_f32_dpp v181, v47, v159 row_shr:2 row_mask:0xf bank_mask:0xf
	v_fmac_f32_dpp v182, v48, v160 row_shr:2 row_mask:0xf bank_mask:0xf
	v_fmac_f32_dpp v183, v49, v161 row_shr:2 row_mask:0xf bank_mask:0xf
	v_fmac_f32_dpp v184, v42, v142 row_shr:2 row_mask:0xf bank_mask:0xf
	v_fmac_f32_dpp v185, v43, v143 row_shr:2 row_mask:0xf bank_mask:0xf
	v_fmac_f32_dpp v186, v44, v144 row_shr:2 row_mask:0xf bank_mask:0xf
	v_fmac_f32_dpp v187, v45, v145 row_shr:2 row_mask:0xf bank_mask:0xf
	v_fmac_f32_dpp v180, v54, v158 row_shl:14 row_mask:0xf bank_mask:0xf
	v_fmac_f32_dpp v181, v55, v159 row_shl:14 row_mask:0xf bank_mask:0xf
	v_fmac_f32_dpp v182, v56, v160 row_shl:14 row_mask:0xf bank_mask:0xf
	v_fmac_f32_dpp v183, v57, v161 row_shl:14 row_mask:0xf bank_mask:0xf
	v_fmac_f32_dpp v184, v50, v142 row_shl:14 row_mask:0xf bank_mask:0xf
	v_fmac_f32_dpp v185, v51, v143 row_shl:14 row_mask:0xf bank_mask:0xf
	v_fmac_f32_dpp v186, v52, v144 row_shl:14 row_mask:0xf bank_mask:0xf
	v_fmac_f32_dpp v187, v53, v145 row_shl:14 row_mask:0xf bank_mask:0xf
; __device__ __forceinline__ void store4(bf16_t* p, f32x4 v) { u32x2 w; w.x = cvt_pk_bf16(v[0], v[1]); w.y = cvt_pk_bf16(v[2], v[3]); *(u32x2*)p = w; }
; __device__ __forceinline__ float dpp_ror1(float x) { float r; asm volatile("s_nop 1\n\tv_mov_b32_dpp %0, %1 row_ror:1 row_mask:0xf bank_mask:0xf" : "=v"(r) : "v"(x)); return r; }
; __device__ __forceinline__ float dpp_ror2(float x) { float r; asm volatile("s_nop 1\n\tv_mov_b32_dpp %0, %1 row_ror:2 row_mask:0xf bank_mask:0xf" : "=v"(r) : "v"(x)); return r; }
;     __device__ __forceinline__ void operator()(const f32x4 (&acc)[2][2][4][2], const Unit& u, int wr, int wc, int fr, int fq) const {
;     ...
; #pragma unroll
;             for (int q = 0; q < 8; ++q) {
;                 const f32x4 ug = acc[q >> 2][0][q & 3][n] * rs[q], uv = acc[q >> 2][1][q & 3][n] * rs[q];
;                 f32x4 res;
; #pragma unroll
;                 for (int j = 0; j < 4; ++j) {
;                     const float ga1 = dpp_ror1(ug[j]), gb1 = dpp_ror1(pg[j]), ga2 = dpp_ror2(ug[j]), gb2 = dpp_ror2(pg[j]);
;                     const float va1 = dpp_ror1(uv[j]), vb1 = dpp_ror1(pv[j]), va2 = dpp_ror2(uv[j]), vb2 = dpp_ror2(pv[j]);
;                     const float g1 = fr >= 1 ? ga1 : gb1, g2 = fr >= 2 ? ga2 : gb2, v1 = fr >= 1 ? va1 : vb1, v2 = fr >= 2 ? va2 : vb2;
;                     const float cgv = bg[j] + wg0[j] * g2 + wg1[j] * g1 + wg2[j] * ug[j];
;                     const float cvv = bv[j] + wv0[j] * v2 + wv1[j] * v1 + wv2[j] * uv[j];
;                     res[j] = cgv * __builtin_amdgcn_rcpf(1.0f + __builtin_amdgcn_exp2f(-1.44269504f * cgv)) * cvv;
;                 }
;                 pg = ug; pv = uv;
;                 const int row = g0 + 16 * q;
;                 if ((q > 0 || fr >= 2) && row < SEQ) store4(ACT + (size_t)row * 2816 + col, res);
	v_fmac_f32_dpp v180, v46, v154 row_shr:1 row_mask:0xf bank_mask:0xf
	v_fmac_f32_dpp v181, v47, v155 row_shr:1 row_mask:0xf bank_mask:0xf
	v_fmac_f32_dpp v182, v48, v156 row_shr:1 row_mask:0xf bank_mask:0xf
	v_fmac_f32_dpp v183, v49, v157 row_shr:1 row_mask:0xf bank_mask:0xf
	v_fmac_f32_dpp v184, v42, v138 row_shr:1 row_mask:0xf bank_mask:0xf
	v_fmac_f32_dpp v185, v43, v139 row_shr:1 row_mask:0xf bank_mask:0xf
	v_fmac_f32_dpp v186, v44, v140 row_shr:1 row_mask:0xf bank_mask:0xf
	v_fmac_f32_dpp v187, v45, v141 row_shr:1 row_mask:0xf bank_mask:0xf
	v_fmac_f32_dpp v180, v54, v154 row_shl:15 row_mask:0xf bank_mask:0xf
	v_fmac_f32_dpp v181, v55, v155 row_shl:15 row_mask:0xf bank_mask:0xf
	v_fmac_f32_dpp v182, v56, v156 row_shl:15 row_mask:0xf bank_mask:0xf
	v_fmac_f32_dpp v183, v57, v157 row_shl:15 row_mask:0xf bank_mask:0xf
	v_fmac_f32_dpp v184, v50, v138 row_shl:15 row_mask:0xf bank_mask:0xf
	v_fmac_f32_dpp v185, v51, v139 row_shl:15 row_mask:0xf bank_mask:0xf
	v_fmac_f32_dpp v186, v52, v140 row_shl:15 row_mask:0xf bank_mask:0xf
	v_fmac_f32_dpp v187, v53, v141 row_shl:15 row_mask:0xf bank_mask:0xf
	v_pk_fma_f32 v[180:181], v[46:47], v[150:151], v[180:181]
	v_pk_fma_f32 v[182:183], v[48:49], v[152:153], v[182:183]
	v_pk_fma_f32 v[184:185], v[42:43], v[134:135], v[184:185]
	v_pk_fma_f32 v[186:187], v[44:45], v[136:137], v[186:187]
	v_pk_mul_f32 v[188:189], v[180:181], s[12:13] op_sel_hi:[1,0]
	v_pk_mul_f32 v[190:191], v[182:183], s[12:13] op_sel_hi:[1,0]
	v_exp_f32_e32 v188, v188
	v_exp_f32_e32 v189, v189
	v_exp_f32_e32 v190, v190
	v_exp_f32_e32 v191, v191
	v_pk_add_f32 v[188:189], v[188:189], 1.0 op_sel_hi:[1,0]
	v_pk_add_f32 v[190:191], v[190:191], 1.0 op_sel_hi:[1,0]
	v_rcp_f32_e32 v188, v188
	v_rcp_f32_e32 v189, v189
	v_rcp_f32_e32 v190, v190
	v_rcp_f32_e32 v191, v191
	v_cmp_gt_i32_e32 vcc, 0x3fe0, v230
	v_pk_mul_f32 v[188:189], v[180:181], v[188:189]
	v_pk_mul_f32 v[190:191], v[182:183], v[190:191]
	v_pk_mul_f32 v[188:189], v[184:185], v[188:189]
	v_pk_mul_f32 v[190:191], v[186:187], v[190:191]
	v_add_u32_e32 v234, 0x2c000, v233
	v_cvt_pk_bf16_f32 v206, v188, v189
	v_cvt_pk_bf16_f32 v207, v190, v191
	s_and_saveexec_b64 s[4:5], vcc
	s_cbranch_execz .Lupepi_skip10
	global_store_dwordx2 v234, v[206:207], s[26:27] offset:8
.Lupepi_skip10:
	s_or_b64 exec, exec, s[4:5]
	v_pk_mul_f32 v[38:39], v[38:39], v[174:175] op_sel:[0,1] op_sel_hi:[1,1]
	v_pk_mul_f32 v[40:41], v[40:41], v[174:175] op_sel:[0,1] op_sel_hi:[1,1]
	v_pk_mul_f32 v[34:35], v[34:35], v[174:175] op_sel:[0,1] op_sel_hi:[1,1]
	v_pk_mul_f32 v[36:37], v[36:37], v[174:175] op_sel:[0,1] op_sel_hi:[1,1]
	v_pk_mov_b32 v[180:181], v[146:147], v[146:147] op_sel:[0,1]
	v_pk_mov_b32 v[182:183], v[148:149], v[148:149] op_sel:[0,1]
	v_pk_mov_b32 v[184:185], v[130:131], v[130:131] op_sel:[0,1]
	v_pk_mov_b32 v[186:187], v[132:133], v[132:133] op_sel:[0,1]
	v_fmac_f32_dpp v180, v38, v158 row_shr:2 row_mask:0xf bank_mask:0xf
	v_fmac_f32_dpp v181, v39, v159 row_shr:2 row_mask:0xf bank_mask:0xf
	v_fmac_f32_dpp v182, v40, v160 row_shr:2 row_mask:0xf bank_mask:0xf
	v_fmac_f32_dpp v183, v41, v161 row_shr:2 row_mask:0xf bank_mask:0xf
	v_fmac_f32_dpp v184, v34, v142 row_shr:2 row_mask:0xf bank_mask:0xf
	v_fmac_f32_dpp v185, v35, v143 row_shr:2 row_mask:0xf bank_mask:0xf
	v_fmac_f32_dpp v186, v36, v144 row_shr:2 row_mask:0xf bank_mask:0xf
	v_fmac_f32_dpp v187, v37, v145 row_shr:2 row_mask:0xf bank_mask:0xf
	v_fmac_f32_dpp v180, v46, v158 row_shl:14 row_mask:0xf bank_mask:0xf
	v_fmac_f32_dpp v181, v47, v159 row_shl:14 row_mask:0xf bank_mask:0xf
	v_fmac_f32_dpp v182, v48, v160 row_shl:14 row_mask:0xf bank_mask:0xf
	v_fmac_f32_dpp v183, v49, v161 row_shl:14 row_mask:0xf bank_mask:0xf
	v_fmac_f32_dpp v184, v42, v142 row_shl:14 row_mask:0xf bank_mask:0xf
	v_fmac_f32_dpp v185, v43, v143 row_shl:14 row_mask:0xf bank_mask:0xf
	v_fmac_f32_dpp v186, v44, v144 row_shl:14 row_mask:0xf bank_mask:0xf
	v_fmac_f32_dpp v187, v45, v145 row_shl:14 row_mask:0xf bank_mask:0xf
	v_fmac_f32_dpp v180, v38, v154 row_shr:1 row_mask:0xf bank_mask:0xf
	v_fmac_f32_dpp v181, v39, v155 row_shr:1 row_mask:0xf bank_mask:0xf
	v_fmac_f32_dpp v182, v40, v156 row_shr:1 row_mask:0xf bank_mask:0xf
	v_fmac_f32_dpp v183, v41, v157 row_shr:1 row_mask:0xf bank_mask:0xf
	v_fmac_f32_dpp v184, v34, v138 row_shr:1 row_mask:0xf bank_mask:0xf
	v_fmac_f32_dpp v185, v35, v139 row_shr:1 row_mask:0xf bank_mask:0xf
	v_fmac_f32_dpp v186, v36, v140 row_shr:1 row_mask:0xf bank_mask:0xf
	v_fmac_f32_dpp v187, v37, v141 row_shr:1 row_mask:0xf bank_mask:0xf
	v_fmac_f32_dpp v180, v46, v154 row_shl:15 row_mask:0xf bank_mask:0xf
	v_fmac_f32_dpp v181, v47, v155 row_shl:15 row_mask:0xf bank_mask:0xf
	v_fmac_f32_dpp v182, v48, v156 row_shl:15 row_mask:0xf bank_mask:0xf
	v_fmac_f32_dpp v183, v49, v157 row_shl:15 row_mask:0xf bank_mask:0xf
	v_fmac_f32_dpp v184, v42, v138 row_shl:15 row_mask:0xf bank_mask:0xf
	v_fmac_f32_dpp v185, v43, v139 row_shl:15 row_mask:0xf bank_mask:0xf
	v_fmac_f32_dpp v186, v44, v140 row_shl:15 row_mask:0xf bank_mask:0xf
	v_fmac_f32_dpp v187, v45, v141 row_shl:15 row_mask:0xf bank_mask:0xf
	v_pk_fma_f32 v[180:181], v[38:39], v[150:151], v[180:181]
	v_pk_fma_f32 v[182:183], v[40:41], v[152:153], v[182:183]
	v_pk_fma_f32 v[184:185], v[34:35], v[134:135], v[184:185]
	v_pk_fma_f32 v[186:187], v[36:37], v[136:137], v[186:187]
	v_pk_mul_f32 v[188:189], v[180:181], s[12:13] op_sel_hi:[1,0]
	v_pk_mul_f32 v[190:191], v[182:183], s[12:13] op_sel_hi:[1,0]
	v_exp_f32_e32 v188, v188
	v_exp_f32_e32 v189, v189
	v_exp_f32_e32 v190, v190
	v_exp_f32_e32 v191, v191
	v_pk_add_f32 v[188:189], v[188:189], 1.0 op_sel_hi:[1,0]
	v_pk_add_f32 v[190:191], v[190:191], 1.0 op_sel_hi:[1,0]
	v_rcp_f32_e32 v188, v188
	v_rcp_f32_e32 v189, v189
	v_rcp_f32_e32 v190, v190
	v_rcp_f32_e32 v191, v191
	v_cmp_gt_i32_e32 vcc, 0x3fd0, v230
	v_pk_mul_f32 v[188:189], v[180:181], v[188:189]
	v_pk_mul_f32 v[190:191], v[182:183], v[190:191]
	v_pk_mul_f32 v[188:189], v[184:185], v[188:189]
	v_pk_mul_f32 v[190:191], v[186:187], v[190:191]
	v_add_u32_e32 v234, 0x42000, v233
	v_cvt_pk_bf16_f32 v208, v188, v189
	v_cvt_pk_bf16_f32 v209, v190, v191
	s_and_saveexec_b64 s[4:5], vcc
	s_cbranch_execz .Lupepi_skip11
	global_store_dwordx2 v234, v[208:209], s[26:27] offset:8
; __device__ __forceinline__ void store4(bf16_t* p, f32x4 v) { u32x2 w; w.x = cvt_pk_bf16(v[0], v[1]); w.y = cvt_pk_bf16(v[2], v[3]); *(u32x2*)p = w; }
; __device__ __forceinline__ float dpp_ror1(float x) { float r; asm volatile("s_nop 1\n\tv_mov_b32_dpp %0, %1 row_ror:1 row_mask:0xf bank_mask:0xf" : "=v"(r) : "v"(x)); return r; }
; __device__ __forceinline__ float dpp_ror2(float x) { float r; asm volatile("s_nop 1\n\tv_mov_b32_dpp %0, %1 row_ror:2 row_mask:0xf bank_mask:0xf" : "=v"(r) : "v"(x)); return r; }
;     __device__ __forceinline__ void operator()(const f32x4 (&acc)[2][2][4][2], const Unit& u, int wr, int wc, int fr, int fq) const {
;     ...
; #pragma unroll
;             for (int q = 0; q < 8; ++q) {
;                 const f32x4 ug = acc[q >> 2][0][q & 3][n] * rs[q], uv = acc[q >> 2][1][q & 3][n] * rs[q];
;                 f32x4 res;
; #pragma unroll
;                 for (int j = 0; j < 4; ++j) {
;                     const float ga1 = dpp_ror1(ug[j]), gb1 = dpp_ror1(pg[j]), ga2 = dpp_ror2(ug[j]), gb2 = dpp_ror2(pg[j]);
;                     const float va1 = dpp_ror1(uv[j]), vb1 = dpp_ror1(pv[j]), va2 = dpp_ror2(uv[j]), vb2 = dpp_ror2(pv[j]);
;                     const float g1 = fr >= 1 ? ga1 : gb1, g2 = fr >= 2 ? ga2 : gb2, v1 = fr >= 1 ? va1 : vb1, v2 = fr >= 2 ? va2 : vb2;
;                     const float cgv = bg[j] + wg0[j] * g2 + wg1[j] * g1 + wg2[j] * ug[j];
;                     const float cvv = bv[j] + wv0[j] * v2 + wv1[j] * v1 + wv2[j] * uv[j];
;                     res[j] = cgv * __builtin_amdgcn_rcpf(1.0f + __builtin_amdgcn_exp2f(-1.44269504f * cgv)) * cvv;
;                 }
;                 pg = ug; pv = uv;
;                 const int row = g0 + 16 * q;
;                 if ((q > 0 || fr >= 2) && row < SEQ) store4(ACT + (size_t)row * 2816 + col, res);
.Lupepi_skip11:
	s_or_b64 exec, exec, s[4:5]
	v_pk_mul_f32 v[30:31], v[30:31], v[176:177] op_sel_hi:[1,0]
	v_pk_mul_f32 v[32:33], v[32:33], v[176:177] op_sel_hi:[1,0]
	v_pk_mul_f32 v[26:27], v[26:27], v[176:177] op_sel_hi:[1,0]
	v_pk_mul_f32 v[28:29], v[28:29], v[176:177] op_sel_hi:[1,0]
	v_pk_mov_b32 v[180:181], v[146:147], v[146:147] op_sel:[0,1]
	v_pk_mov_b32 v[182:183], v[148:149], v[148:149] op_sel:[0,1]
	v_pk_mov_b32 v[184:185], v[130:131], v[130:131] op_sel:[0,1]
	v_pk_mov_b32 v[186:187], v[132:133], v[132:133] op_sel:[0,1]
	v_fmac_f32_dpp v180, v30, v158 row_shr:2 row_mask:0xf bank_mask:0xf
	v_fmac_f32_dpp v181, v31, v159 row_shr:2 row_mask:0xf bank_mask:0xf
	v_fmac_f32_dpp v182, v32, v160 row_shr:2 row_mask:0xf bank_mask:0xf
	v_fmac_f32_dpp v183, v33, v161 row_shr:2 row_mask:0xf bank_mask:0xf
	v_fmac_f32_dpp v184, v26, v142 row_shr:2 row_mask:0xf bank_mask:0xf
	v_fmac_f32_dpp v185, v27, v143 row_shr:2 row_mask:0xf bank_mask:0xf
	v_fmac_f32_dpp v186, v28, v144 row_shr:2 row_mask:0xf bank_mask:0xf
	v_fmac_f32_dpp v187, v29, v145 row_shr:2 row_mask:0xf bank_mask:0xf
	v_fmac_f32_dpp v180, v38, v158 row_shl:14 row_mask:0xf bank_mask:0xf
	v_fmac_f32_dpp v181, v39, v159 row_shl:14 row_mask:0xf bank_mask:0xf
	v_fmac_f32_dpp v182, v40, v160 row_shl:14 row_mask:0xf bank_mask:0xf
	v_fmac_f32_dpp v183, v41, v161 row_shl:14 row_mask:0xf bank_mask:0xf
	v_fmac_f32_dpp v184, v34, v142 row_shl:14 row_mask:0xf bank_mask:0xf
	v_fmac_f32_dpp v185, v35, v143 row_shl:14 row_mask:0xf bank_mask:0xf
	v_fmac_f32_dpp v186, v36, v144 row_shl:14 row_mask:0xf bank_mask:0xf
	v_fmac_f32_dpp v187, v37, v145 row_shl:14 row_mask:0xf bank_mask:0xf
	v_fmac_f32_dpp v180, v30, v154 row_shr:1 row_mask:0xf bank_mask:0xf
	v_fmac_f32_dpp v181, v31, v155 row_shr:1 row_mask:0xf bank_mask:0xf
	v_fmac_f32_dpp v182, v32, v156 row_shr:1 row_mask:0xf bank_mask:0xf
	v_fmac_f32_dpp v183, v33, v157 row_shr:1 row_mask:0xf bank_mask:0xf
	v_fmac_f32_dpp v184, v26, v138 row_shr:1 row_mask:0xf bank_mask:0xf
	v_fmac_f32_dpp v185, v27, v139 row_shr:1 row_mask:0xf bank_mask:0xf
	v_fmac_f32_dpp v186, v28, v140 row_shr:1 row_mask:0xf bank_mask:0xf
	v_fmac_f32_dpp v187, v29, v141 row_shr:1 row_mask:0xf bank_mask:0xf
	v_fmac_f32_dpp v180, v38, v154 row_shl:15 row_mask:0xf bank_mask:0xf
	v_fmac_f32_dpp v181, v39, v155 row_shl:15 row_mask:0xf bank_mask:0xf
	v_fmac_f32_dpp v182, v40, v156 row_shl:15 row_mask:0xf bank_mask:0xf
	v_fmac_f32_dpp v183, v41, v157 row_shl:15 row_mask:0xf bank_mask:0xf
	v_fmac_f32_dpp v184, v34, v138 row_shl:15 row_mask:0xf bank_mask:0xf
	v_fmac_f32_dpp v185, v35, v139 row_shl:15 row_mask:0xf bank_mask:0xf
	v_fmac_f32_dpp v186, v36, v140 row_shl:15 row_mask:0xf bank_mask:0xf
	v_fmac_f32_dpp v187, v37, v141 row_shl:15 row_mask:0xf bank_mask:0xf
	v_pk_fma_f32 v[180:181], v[30:31], v[150:151], v[180:181]
	v_pk_fma_f32 v[182:183], v[32:33], v[152:153], v[182:183]
	v_pk_fma_f32 v[184:185], v[26:27], v[134:135], v[184:185]
	v_pk_fma_f32 v[186:187], v[28:29], v[136:137], v[186:187]
	v_pk_mul_f32 v[188:189], v[180:181], s[12:13] op_sel_hi:[1,0]
	v_pk_mul_f32 v[190:191], v[182:183], s[12:13] op_sel_hi:[1,0]
	v_exp_f32_e32 v188, v188
	v_exp_f32_e32 v189, v189
	v_exp_f32_e32 v190, v190
	v_exp_f32_e32 v191, v191
	v_pk_add_f32 v[188:189], v[188:189], 1.0 op_sel_hi:[1,0]
	v_pk_add_f32 v[190:191], v[190:191], 1.0 op_sel_hi:[1,0]
	v_rcp_f32_e32 v188, v188
	v_rcp_f32_e32 v189, v189
	v_rcp_f32_e32 v190, v190
	v_rcp_f32_e32 v191, v191
	v_cmp_gt_i32_e32 vcc, 0x3fc0, v230
	v_pk_mul_f32 v[188:189], v[180:181], v[188:189]
	v_pk_mul_f32 v[190:191], v[182:183], v[190:191]
	v_pk_mul_f32 v[188:189], v[184:185], v[188:189]
	v_pk_mul_f32 v[190:191], v[186:187], v[190:191]
	v_add_u32_e32 v234, 0x58000, v233
	v_cvt_pk_bf16_f32 v206, v188, v189
	v_cvt_pk_bf16_f32 v207, v190, v191
	s_and_saveexec_b64 s[4:5], vcc
	s_cbranch_execz .Lupepi_skip12
	global_store_dwordx2 v234, v[206:207], s[26:27] offset:8
.Lupepi_skip12:
	s_or_b64 exec, exec, s[4:5]
	v_pk_mul_f32 v[22:23], v[22:23], v[176:177] op_sel:[0,1] op_sel_hi:[1,1]
	v_pk_mul_f32 v[24:25], v[24:25], v[176:177] op_sel:[0,1] op_sel_hi:[1,1]
	v_pk_mul_f32 v[18:19], v[18:19], v[176:177] op_sel:[0,1] op_sel_hi:[1,1]
	v_pk_mul_f32 v[20:21], v[20:21], v[176:177] op_sel:[0,1] op_sel_hi:[1,1]
	v_pk_mov_b32 v[180:181], v[146:147], v[146:147] op_sel:[0,1]
	v_pk_mov_b32 v[182:183], v[148:149], v[148:149] op_sel:[0,1]
	v_pk_mov_b32 v[184:185], v[130:131], v[130:131] op_sel:[0,1]
	v_pk_mov_b32 v[186:187], v[132:133], v[132:133] op_sel:[0,1]
	v_fmac_f32_dpp v180, v22, v158 row_shr:2 row_mask:0xf bank_mask:0xf
	v_fmac_f32_dpp v181, v23, v159 row_shr:2 row_mask:0xf bank_mask:0xf
	v_fmac_f32_dpp v182, v24, v160 row_shr:2 row_mask:0xf bank_mask:0xf
	v_fmac_f32_dpp v183, v25, v161 row_shr:2 row_mask:0xf bank_mask:0xf
	v_fmac_f32_dpp v184, v18, v142 row_shr:2 row_mask:0xf bank_mask:0xf
	v_fmac_f32_dpp v185, v19, v143 row_shr:2 row_mask:0xf bank_mask:0xf
	v_fmac_f32_dpp v186, v20, v144 row_shr:2 row_mask:0xf bank_mask:0xf
	v_fmac_f32_dpp v187, v21, v145 row_shr:2 row_mask:0xf bank_mask:0xf
	v_fmac_f32_dpp v180, v30, v158 row_shl:14 row_mask:0xf bank_mask:0xf
	v_fmac_f32_dpp v181, v31, v159 row_shl:14 row_mask:0xf bank_mask:0xf
	v_fmac_f32_dpp v182, v32, v160 row_shl:14 row_mask:0xf bank_mask:0xf
	v_fmac_f32_dpp v183, v33, v161 row_shl:14 row_mask:0xf bank_mask:0xf
	v_fmac_f32_dpp v184, v26, v142 row_shl:14 row_mask:0xf bank_mask:0xf
	v_fmac_f32_dpp v185, v27, v143 row_shl:14 row_mask:0xf bank_mask:0xf
	v_fmac_f32_dpp v186, v28, v144 row_shl:14 row_mask:0xf bank_mask:0xf
	v_fmac_f32_dpp v187, v29, v145 row_shl:14 row_mask:0xf bank_mask:0xf
; __device__ __forceinline__ void store4(bf16_t* p, f32x4 v) { u32x2 w; w.x = cvt_pk_bf16(v[0], v[1]); w.y = cvt_pk_bf16(v[2], v[3]); *(u32x2*)p = w; }
; __device__ __forceinline__ float dpp_ror1(float x) { float r; asm volatile("s_nop 1\n\tv_mov_b32_dpp %0, %1 row_ror:1 row_mask:0xf bank_mask:0xf" : "=v"(r) : "v"(x)); return r; }
; __device__ __forceinline__ float dpp_ror2(float x) { float r; asm volatile("s_nop 1\n\tv_mov_b32_dpp %0, %1 row_ror:2 row_mask:0xf bank_mask:0xf" : "=v"(r) : "v"(x)); return r; }
;     __device__ __forceinline__ void operator()(const f32x4 (&acc)[2][2][4][2], const Unit& u, int wr, int wc, int fr, int fq) const {
;     ...
; #pragma unroll
;             for (int q = 0; q < 8; ++q) {
;                 const f32x4 ug = acc[q >> 2][0][q & 3][n] * rs[q], uv = acc[q >> 2][1][q & 3][n] * rs[q];
;                 f32x4 res;
; #pragma unroll
;                 for (int j = 0; j < 4; ++j) {
;                     const float ga1 = dpp_ror1(ug[j]), gb1 = dpp_ror1(pg[j]), ga2 = dpp_ror2(ug[j]), gb2 = dpp_ror2(pg[j]);
;                     const float va1 = dpp_ror1(uv[j]), vb1 = dpp_ror1(pv[j]), va2 = dpp_ror2(uv[j]), vb2 = dpp_ror2(pv[j]);
;                     const float g1 = fr >= 1 ? ga1 : gb1, g2 = fr >= 2 ? ga2 : gb2, v1 = fr >= 1 ? va1 : vb1, v2 = fr >= 2 ? va2 : vb2;
;                     const float cgv = bg[j] + wg0[j] * g2 + wg1[j] * g1 + wg2[j] * ug[j];
;                     const float cvv = bv[j] + wv0[j] * v2 + wv1[j] * v1 + wv2[j] * uv[j];
;                     res[j] = cgv * __builtin_amdgcn_rcpf(1.0f + __builtin_amdgcn_exp2f(-1.44269504f * cgv)) * cvv;
;                 }
;                 pg = ug; pv = uv;
;                 const int row = g0 + 16 * q;
;                 if ((q > 0 || fr >= 2) && row < SEQ) store4(ACT + (size_t)row * 2816 + col, res);
	v_fmac_f32_dpp v180, v22, v154 row_shr:1 row_mask:0xf bank_mask:0xf
	v_fmac_f32_dpp v181, v23, v155 row_shr:1 row_mask:0xf bank_mask:0xf
	v_fmac_f32_dpp v182, v24, v156 row_shr:1 row_mask:0xf bank_mask:0xf
	v_fmac_f32_dpp v183, v25, v157 row_shr:1 row_mask:0xf bank_mask:0xf
	v_fmac_f32_dpp v184, v18, v138 row_shr:1 row_mask:0xf bank_mask:0xf
	v_fmac_f32_dpp v185, v19, v139 row_shr:1 row_mask:0xf bank_mask:0xf
	v_fmac_f32_dpp v186, v20, v140 row_shr:1 row_mask:0xf bank_mask:0xf
	v_fmac_f32_dpp v187, v21, v141 row_shr:1 row_mask:0xf bank_mask:0xf
	v_fmac_f32_dpp v180, v30, v154 row_shl:15 row_mask:0xf bank_mask:0xf
	v_fmac_f32_dpp v181, v31, v155 row_shl:15 row_mask:0xf bank_mask:0xf
	v_fmac_f32_dpp v182, v32, v156 row_shl:15 row_mask:0xf bank_mask:0xf
	v_fmac_f32_dpp v183, v33, v157 row_shl:15 row_mask:0xf bank_mask:0xf
	v_fmac_f32_dpp v184, v26, v138 row_shl:15 row_mask:0xf bank_mask:0xf
	v_fmac_f32_dpp v185, v27, v139 row_shl:15 row_mask:0xf bank_mask:0xf
	v_fmac_f32_dpp v186, v28, v140 row_shl:15 row_mask:0xf bank_mask:0xf
	v_fmac_f32_dpp v187, v29, v141 row_shl:15 row_mask:0xf bank_mask:0xf
	v_pk_fma_f32 v[180:181], v[22:23], v[150:151], v[180:181]
	v_pk_fma_f32 v[182:183], v[24:25], v[152:153], v[182:183]
	v_pk_fma_f32 v[184:185], v[18:19], v[134:135], v[184:185]
	v_pk_fma_f32 v[186:187], v[20:21], v[136:137], v[186:187]
	v_pk_mul_f32 v[188:189], v[180:181], s[12:13] op_sel_hi:[1,0]
	v_pk_mul_f32 v[190:191], v[182:183], s[12:13] op_sel_hi:[1,0]
	v_exp_f32_e32 v188, v188
	v_exp_f32_e32 v189, v189
	v_exp_f32_e32 v190, v190
	v_exp_f32_e32 v191, v191
	v_pk_add_f32 v[188:189], v[188:189], 1.0 op_sel_hi:[1,0]
	v_pk_add_f32 v[190:191], v[190:191], 1.0 op_sel_hi:[1,0]
	v_rcp_f32_e32 v188, v188
	v_rcp_f32_e32 v189, v189
	v_rcp_f32_e32 v190, v190
	v_rcp_f32_e32 v191, v191
	v_cmp_gt_i32_e32 vcc, 0x3fb0, v230
	v_pk_mul_f32 v[188:189], v[180:181], v[188:189]
	v_pk_mul_f32 v[190:191], v[182:183], v[190:191]
	v_pk_mul_f32 v[188:189], v[184:185], v[188:189]
	v_pk_mul_f32 v[190:191], v[186:187], v[190:191]
	v_add_u32_e32 v234, 0x6e000, v233
	v_cvt_pk_bf16_f32 v208, v188, v189
	v_cvt_pk_bf16_f32 v209, v190, v191
	s_and_saveexec_b64 s[4:5], vcc
	s_cbranch_execz .Lupepi_skip13
	global_store_dwordx2 v234, v[208:209], s[26:27] offset:8
.Lupepi_skip13:
	s_or_b64 exec, exec, s[4:5]
	v_pk_mul_f32 v[14:15], v[14:15], v[178:179] op_sel_hi:[1,0]
	v_pk_mul_f32 v[16:17], v[16:17], v[178:179] op_sel_hi:[1,0]
	v_pk_mul_f32 v[10:11], v[10:11], v[178:179] op_sel_hi:[1,0]
	v_pk_mul_f32 v[12:13], v[12:13], v[178:179] op_sel_hi:[1,0]
	v_pk_mov_b32 v[180:181], v[146:147], v[146:147] op_sel:[0,1]
	v_pk_mov_b32 v[182:183], v[148:149], v[148:149] op_sel:[0,1]
	v_pk_mov_b32 v[184:185], v[130:131], v[130:131] op_sel:[0,1]
	v_pk_mov_b32 v[186:187], v[132:133], v[132:133] op_sel:[0,1]
	v_fmac_f32_dpp v180, v14, v158 row_shr:2 row_mask:0xf bank_mask:0xf
	v_fmac_f32_dpp v181, v15, v159 row_shr:2 row_mask:0xf bank_mask:0xf
	v_fmac_f32_dpp v182, v16, v160 row_shr:2 row_mask:0xf bank_mask:0xf
	v_fmac_f32_dpp v183, v17, v161 row_shr:2 row_mask:0xf bank_mask:0xf
	v_fmac_f32_dpp v184, v10, v142 row_shr:2 row_mask:0xf bank_mask:0xf
	v_fmac_f32_dpp v185, v11, v143 row_shr:2 row_mask:0xf bank_mask:0xf
	v_fmac_f32_dpp v186, v12, v144 row_shr:2 row_mask:0xf bank_mask:0xf
	v_fmac_f32_dpp v187, v13, v145 row_shr:2 row_mask:0xf bank_mask:0xf
	v_fmac_f32_dpp v180, v22, v158 row_shl:14 row_mask:0xf bank_mask:0xf
	v_fmac_f32_dpp v181, v23, v159 row_shl:14 row_mask:0xf bank_mask:0xf
	v_fmac_f32_dpp v182, v24, v160 row_shl:14 row_mask:0xf bank_mask:0xf
	v_fmac_f32_dpp v183, v25, v161 row_shl:14 row_mask:0xf bank_mask:0xf
	v_fmac_f32_dpp v184, v18, v142 row_shl:14 row_mask:0xf bank_mask:0xf
	v_fmac_f32_dpp v185, v19, v143 row_shl:14 row_mask:0xf bank_mask:0xf
	v_fmac_f32_dpp v186, v20, v144 row_shl:14 row_mask:0xf bank_mask:0xf
	v_fmac_f32_dpp v187, v21, v145 row_shl:14 row_mask:0xf bank_mask:0xf
	v_fmac_f32_dpp v180, v14, v154 row_shr:1 row_mask:0xf bank_mask:0xf
	v_fmac_f32_dpp v181, v15, v155 row_shr:1 row_mask:0xf bank_mask:0xf
	v_fmac_f32_dpp v182, v16, v156 row_shr:1 row_mask:0xf bank_mask:0xf
	v_fmac_f32_dpp v183, v17, v157 row_shr:1 row_mask:0xf bank_mask:0xf
	v_fmac_f32_dpp v184, v10, v138 row_shr:1 row_mask:0xf bank_mask:0xf
	v_fmac_f32_dpp v185, v11, v139 row_shr:1 row_mask:0xf bank_mask:0xf
	v_fmac_f32_dpp v186, v12, v140 row_shr:1 row_mask:0xf bank_mask:0xf
	v_fmac_f32_dpp v187, v13, v141 row_shr:1 row_mask:0xf bank_mask:0xf
	v_fmac_f32_dpp v180, v22, v154 row_shl:15 row_mask:0xf bank_mask:0xf
	v_fmac_f32_dpp v181, v23, v155 row_shl:15 row_mask:0xf bank_mask:0xf
	v_fmac_f32_dpp v182, v24, v156 row_shl:15 row_mask:0xf bank_mask:0xf
	v_fmac_f32_dpp v183, v25, v157 row_shl:15 row_mask:0xf bank_mask:0xf
	v_fmac_f32_dpp v184, v18, v138 row_shl:15 row_mask:0xf bank_mask:0xf
	v_fmac_f32_dpp v185, v19, v139 row_shl:15 row_mask:0xf bank_mask:0xf
	v_fmac_f32_dpp v186, v20, v140 row_shl:15 row_mask:0xf bank_mask:0xf
	v_fmac_f32_dpp v187, v21, v141 row_shl:15 row_mask:0xf bank_mask:0xf
	v_pk_fma_f32 v[180:181], v[14:15], v[150:151], v[180:181]
	v_pk_fma_f32 v[182:183], v[16:17], v[152:153], v[182:183]
	v_pk_fma_f32 v[184:185], v[10:11], v[134:135], v[184:185]
	v_pk_fma_f32 v[186:187], v[12:13], v[136:137], v[186:187]
	v_pk_mul_f32 v[188:189], v[180:181], s[12:13] op_sel_hi:[1,0]
	v_pk_mul_f32 v[190:191], v[182:183], s[12:13] op_sel_hi:[1,0]
	v_exp_f32_e32 v188, v188
	v_exp_f32_e32 v189, v189
	v_exp_f32_e32 v190, v190
	v_exp_f32_e32 v191, v191
	v_pk_add_f32 v[188:189], v[188:189], 1.0 op_sel_hi:[1,0]
	v_pk_add_f32 v[190:191], v[190:191], 1.0 op_sel_hi:[1,0]
	v_rcp_f32_e32 v188, v188
	v_rcp_f32_e32 v189, v189
	v_rcp_f32_e32 v190, v190
	v_rcp_f32_e32 v191, v191
	v_cmp_gt_i32_e32 vcc, 0x3fa0, v230
	v_pk_mul_f32 v[188:189], v[180:181], v[188:189]
	v_pk_mul_f32 v[190:191], v[182:183], v[190:191]
	v_pk_mul_f32 v[188:189], v[184:185], v[188:189]
	v_pk_mul_f32 v[190:191], v[186:187], v[190:191]
	v_add_u32_e32 v234, 0x84000, v233
	v_cvt_pk_bf16_f32 v206, v188, v189
	v_cvt_pk_bf16_f32 v207, v190, v191
	s_and_saveexec_b64 s[4:5], vcc
	s_cbranch_execz .Lupepi_skip14
	global_store_dwordx2 v234, v[206:207], s[26:27] offset:8
; __device__ __forceinline__ void store4(bf16_t* p, f32x4 v) { u32x2 w; w.x = cvt_pk_bf16(v[0], v[1]); w.y = cvt_pk_bf16(v[2], v[3]); *(u32x2*)p = w; }
; __device__ __forceinline__ float dpp_ror1(float x) { float r; asm volatile("s_nop 1\n\tv_mov_b32_dpp %0, %1 row_ror:1 row_mask:0xf bank_mask:0xf" : "=v"(r) : "v"(x)); return r; }
; __device__ __forceinline__ float dpp_ror2(float x) { float r; asm volatile("s_nop 1\n\tv_mov_b32_dpp %0, %1 row_ror:2 row_mask:0xf bank_mask:0xf" : "=v"(r) : "v"(x)); return r; }
;     __device__ __forceinline__ void operator()(const f32x4 (&acc)[2][2][4][2], const Unit& u, int wr, int wc, int fr, int fq) const {
;     ...
; #pragma unroll
;             for (int q = 0; q < 8; ++q) {
;                 const f32x4 ug = acc[q >> 2][0][q & 3][n] * rs[q], uv = acc[q >> 2][1][q & 3][n] * rs[q];
;                 f32x4 res;
; #pragma unroll
;                 for (int j = 0; j < 4; ++j) {
;                     const float ga1 = dpp_ror1(ug[j]), gb1 = dpp_ror1(pg[j]), ga2 = dpp_ror2(ug[j]), gb2 = dpp_ror2(pg[j]);
;                     const float va1 = dpp_ror1(uv[j]), vb1 = dpp_ror1(pv[j]), va2 = dpp_ror2(uv[j]), vb2 = dpp_ror2(pv[j]);
;                     const float g1 = fr >= 1 ? ga1 : gb1, g2 = fr >= 2 ? ga2 : gb2, v1 = fr >= 1 ? va1 : vb1, v2 = fr >= 2 ? va2 : vb2;
;                     const float cgv = bg[j] + wg0[j] * g2 + wg1[j] * g1 + wg2[j] * ug[j];
;                     const float cvv = bv[j] + wv0[j] * v2 + wv1[j] * v1 + wv2[j] * uv[j];
;                     res[j] = cgv * __builtin_amdgcn_rcpf(1.0f + __builtin_amdgcn_exp2f(-1.44269504f * cgv)) * cvv;
;                 }
;                 pg = ug; pv = uv;
;                 const int row = g0 + 16 * q;
;                 if ((q > 0 || fr >= 2) && row < SEQ) store4(ACT + (size_t)row * 2816 + col, res);
.Lupepi_skip14:
	s_or_b64 exec, exec, s[4:5]
	v_pk_mul_f32 v[6:7], v[6:7], v[178:179] op_sel:[0,1] op_sel_hi:[1,1]
	v_pk_mul_f32 v[8:9], v[8:9], v[178:179] op_sel:[0,1] op_sel_hi:[1,1]
	v_pk_mul_f32 v[2:3], v[2:3], v[178:179] op_sel:[0,1] op_sel_hi:[1,1]
	v_pk_mul_f32 v[4:5], v[4:5], v[178:179] op_sel:[0,1] op_sel_hi:[1,1]
	v_pk_mov_b32 v[180:181], v[146:147], v[146:147] op_sel:[0,1]
	v_pk_mov_b32 v[182:183], v[148:149], v[148:149] op_sel:[0,1]
	v_pk_mov_b32 v[184:185], v[130:131], v[130:131] op_sel:[0,1]
	v_pk_mov_b32 v[186:187], v[132:133], v[132:133] op_sel:[0,1]
	v_fmac_f32_dpp v180, v6, v158 row_shr:2 row_mask:0xf bank_mask:0xf
	v_fmac_f32_dpp v181, v7, v159 row_shr:2 row_mask:0xf bank_mask:0xf
	v_fmac_f32_dpp v182, v8, v160 row_shr:2 row_mask:0xf bank_mask:0xf
	v_fmac_f32_dpp v183, v9, v161 row_shr:2 row_mask:0xf bank_mask:0xf
	v_fmac_f32_dpp v184, v2, v142 row_shr:2 row_mask:0xf bank_mask:0xf
	v_fmac_f32_dpp v185, v3, v143 row_shr:2 row_mask:0xf bank_mask:0xf
	v_fmac_f32_dpp v186, v4, v144 row_shr:2 row_mask:0xf bank_mask:0xf
	v_fmac_f32_dpp v187, v5, v145 row_shr:2 row_mask:0xf bank_mask:0xf
	v_fmac_f32_dpp v180, v14, v158 row_shl:14 row_mask:0xf bank_mask:0xf
	v_fmac_f32_dpp v181, v15, v159 row_shl:14 row_mask:0xf bank_mask:0xf
	v_fmac_f32_dpp v182, v16, v160 row_shl:14 row_mask:0xf bank_mask:0xf
	v_fmac_f32_dpp v183, v17, v161 row_shl:14 row_mask:0xf bank_mask:0xf
	v_fmac_f32_dpp v184, v10, v142 row_shl:14 row_mask:0xf bank_mask:0xf
	v_fmac_f32_dpp v185, v11, v143 row_shl:14 row_mask:0xf bank_mask:0xf
	v_fmac_f32_dpp v186, v12, v144 row_shl:14 row_mask:0xf bank_mask:0xf
	v_fmac_f32_dpp v187, v13, v145 row_shl:14 row_mask:0xf bank_mask:0xf
	v_fmac_f32_dpp v180, v6, v154 row_shr:1 row_mask:0xf bank_mask:0xf
	v_fmac_f32_dpp v181, v7, v155 row_shr:1 row_mask:0xf bank_mask:0xf
	v_fmac_f32_dpp v182, v8, v156 row_shr:1 row_mask:0xf bank_mask:0xf
	v_fmac_f32_dpp v183, v9, v157 row_shr:1 row_mask:0xf bank_mask:0xf
	v_fmac_f32_dpp v184, v2, v138 row_shr:1 row_mask:0xf bank_mask:0xf
	v_fmac_f32_dpp v185, v3, v139 row_shr:1 row_mask:0xf bank_mask:0xf
	v_fmac_f32_dpp v186, v4, v140 row_shr:1 row_mask:0xf bank_mask:0xf
	v_fmac_f32_dpp v187, v5, v141 row_shr:1 row_mask:0xf bank_mask:0xf
	v_fmac_f32_dpp v180, v14, v154 row_shl:15 row_mask:0xf bank_mask:0xf
	v_fmac_f32_dpp v181, v15, v155 row_shl:15 row_mask:0xf bank_mask:0xf
	v_fmac_f32_dpp v182, v16, v156 row_shl:15 row_mask:0xf bank_mask:0xf
	v_fmac_f32_dpp v183, v17, v157 row_shl:15 row_mask:0xf bank_mask:0xf
	v_fmac_f32_dpp v184, v10, v138 row_shl:15 row_mask:0xf bank_mask:0xf
	v_fmac_f32_dpp v185, v11, v139 row_shl:15 row_mask:0xf bank_mask:0xf
	v_fmac_f32_dpp v186, v12, v140 row_shl:15 row_mask:0xf bank_mask:0xf
	v_fmac_f32_dpp v187, v13, v141 row_shl:15 row_mask:0xf bank_mask:0xf
	v_pk_fma_f32 v[180:181], v[6:7], v[150:151], v[180:181]
	v_pk_fma_f32 v[182:183], v[8:9], v[152:153], v[182:183]
	v_pk_fma_f32 v[184:185], v[2:3], v[134:135], v[184:185]
	v_pk_fma_f32 v[186:187], v[4:5], v[136:137], v[186:187]
	v_pk_mul_f32 v[188:189], v[180:181], s[12:13] op_sel_hi:[1,0]
	v_pk_mul_f32 v[190:191], v[182:183], s[12:13] op_sel_hi:[1,0]
	v_exp_f32_e32 v188, v188
	v_exp_f32_e32 v189, v189
	v_exp_f32_e32 v190, v190
	v_exp_f32_e32 v191, v191
	v_pk_add_f32 v[188:189], v[188:189], 1.0 op_sel_hi:[1,0]
	v_pk_add_f32 v[190:191], v[190:191], 1.0 op_sel_hi:[1,0]
	v_rcp_f32_e32 v188, v188
	v_rcp_f32_e32 v189, v189
	v_rcp_f32_e32 v190, v190
	v_rcp_f32_e32 v191, v191
	v_cmp_gt_i32_e32 vcc, 0x3f90, v230
	v_pk_mul_f32 v[188:189], v[180:181], v[188:189]
	v_pk_mul_f32 v[190:191], v[182:183], v[190:191]
	v_pk_mul_f32 v[188:189], v[184:185], v[188:189]
	v_pk_mul_f32 v[190:191], v[186:187], v[190:191]
	v_add_u32_e32 v234, 0x9a000, v233
	v_cvt_pk_bf16_f32 v208, v188, v189
	v_cvt_pk_bf16_f32 v209, v190, v191
	s_and_saveexec_b64 s[4:5], vcc
	s_cbranch_execz .LBB0_2355
	global_store_dwordx2 v234, v[208:209], s[26:27] offset:8
